# UPCONV epilogue groups padded to start at 0 mod 8 bytes; K-loop heads 64-byte aligned
# baseline (speedup 1.0000x reference)
;     __device__ __forceinline__ void operator()(const f32x4 (&acc)[2][2][4][2], const Unit& u, int wr, int wc, int fr, int fq) const {
;     ...
;                 for (int m = 0; m < 4; ++m) rs[ai][m] = rsqrtf(ss[row0 + ai * HALF + m * 16] * (1.f / 2048.f) + 1e-6f);
; #pragma unroll
;             for (int ai = 0; ai < 2; ++ai) {
;                 const int slab = u.pm * 4 + ai * 2 + wr;
;                 if (fr < 2) {
; #pragma unroll
;                     for (int bj = 0; bj < 2; ++bj)
; #pragma unroll
;                         for (int n = 0; n < 2; ++n) *(f32x4*)(raw + (size_t)(slab * 4 + fr) * NUPc + tcol + bj * 128 + 4 * n) = acc[ai][bj][0][n] * rs[ai][0];
;                 }
;                 if (fr >= 14) {
; #pragma unroll
;                     for (int bj = 0; bj < 2; ++bj)
; #pragma unroll
;                         for (int n = 0; n < 2; ++n) *(f32x4*)(raw + (size_t)(slab * 4 + fr - 12) * NUPc + tcol + bj * 128 + 4 * n) = acc[ai][bj][3][n] * rs[ai][3];
;                 }
;             }
; #pragma unroll
;             for (int n = 0; n < 2; ++n) {
;                 const int c = cgl + 4 * n;
;                 const f32x4 wg0 = *(const f32x4*)(bias + c), wg1 = *(const f32x4*)(bias + NUPc + c), wg2 = *(const f32x4*)(bias + 2 * NUPc + c), bg = *(const f32x4*)(xin + c);
;                 const f32x4 wv0 = *(const f32x4*)(bias + DFFc + c), wv1 = *(const f32x4*)(bias + NUPc + DFFc + c), wv2 = *(const f32x4*)(bias + 2 * NUPc + DFFc + c), bv = *(const f32x4*)(xin + DFFc + c);
; #pragma unroll
;                 for (int ai = 0; ai < 2; ++ai) {
;                     f32x4 pg1 = (f32x4){0.f, 0.f, 0.f, 0.f}, pg2 = pg1, pv1 = pg1, pv2 = pg1;
; #pragma unroll
;                     for (int m = 0; m < 4; ++m) {
;                         const f32x4 g = acc[ai][0][m][n] * rs[ai][m], v = acc[ai][1][m][n] * rs[ai][m];
;                         const f32x4 g1 = dpp4<0x121>(g), g2 = dpp4<0x122>(g), v1 = dpp4<0x121>(v), v2 = dpp4<0x122>(v);
;                         const f32x4 gp1 = (fr >= 1) ? g1 : pg1, gp2 = (fr >= 2) ? g2 : pg2, vp1 = (fr >= 1) ? v1 : pv1, vp2 = (fr >= 2) ? v2 : pv2;
;                         const f32x4 cgt = bg + wg0 * g + wg1 * gp1 + wg2 * gp2, cvl = bv + wv0 * v + wv1 * vp1 + wv2 * vp2;
;                         const f32x4 o = gelu4(cgt) * cvl;
;                         typedef unsigned u32x2e __attribute__((ext_vector_type(2)));
.LBB0_54:
	s_or_b64 exec, exec, s[48:49]
	v_fmamk_f32 v187, v187, 0x3a000000, v197
	v_fmamk_f32 v179, v179, 0x3a000000, v197
	v_fmamk_f32 v185, v185, 0x3a000000, v197
	v_fmamk_f32 v183, v183, 0x3a000000, v197
	v_cmp_gt_f32_e32 vcc, s67, v187
	v_cmp_gt_f32_e64 s[48:49], s67, v179
	v_cmp_gt_f32_e64 s[50:51], s67, v185
	v_cmp_gt_f32_e64 s[52:53], s67, v183
	v_mul_f32_e32 v181, 0x4b800000, v187
	v_mul_f32_e32 v189, 0x4b800000, v179
	v_mul_f32_e32 v191, 0x4b800000, v185
	v_mul_f32_e32 v193, 0x4b800000, v183
	v_cndmask_b32_e32 v187, v187, v181, vcc
	v_cndmask_b32_e64 v179, v179, v189, s[48:49]
	v_cndmask_b32_e64 v185, v185, v191, s[50:51]
	v_cndmask_b32_e64 v183, v183, v193, s[52:53]
	v_rsq_f32_e32 v187, v187
	v_rsq_f32_e32 v179, v179
	v_rsq_f32_e32 v185, v185
	v_rsq_f32_e32 v183, v183
	v_mul_f32_e32 v181, 0x45800000, v187
	v_mul_f32_e32 v189, 0x45800000, v179
	v_mul_f32_e32 v191, 0x45800000, v185
	v_mul_f32_e32 v193, 0x45800000, v183
	v_cndmask_b32_e32 v190, v187, v181, vcc
	v_cndmask_b32_e64 v192, v179, v189, s[48:49]
	v_cndmask_b32_e64 v180, v185, v191, s[50:51]
	v_cndmask_b32_e64 v200, v183, v193, s[52:53]
	v_mov_b32_e32 v132, 0xbdd2d3e8
	v_mov_b32_e32 v250, 1.0
	v_lshlrev_b32_e32 v199, 1, v201
	s_movk_i32 s41, 0x2c00
	v_mad_u32_u24 v199, v186, s41, v199
	v_pk_mul_f32 v[154:155], v[154:155], v[188:189] op_sel_hi:[1,0]
	v_pk_mul_f32 v[156:157], v[156:157], v[188:189] op_sel_hi:[1,0]
	v_pk_mul_f32 v[134:135], v[134:135], v[188:189] op_sel_hi:[1,0]
	v_pk_mul_f32 v[136:137], v[136:137], v[188:189] op_sel_hi:[1,0]
	v_pk_fma_f32 v[106:107], v[154:155], v[218:219], v[222:223]
	v_pk_fma_f32 v[108:109], v[156:157], v[220:221], v[224:225]
	v_pk_fma_f32 v[110:111], v[134:135], v[234:235], v[238:239]
	v_pk_fma_f32 v[112:113], v[136:137], v[236:237], v[240:241]
	v_fmac_f32_dpp v106, v154, v226 row_shr:1 row_mask:0xf bank_mask:0xf
	v_fmac_f32_dpp v107, v155, v227 row_shr:1 row_mask:0xf bank_mask:0xf
	v_fmac_f32_dpp v108, v156, v228 row_shr:1 row_mask:0xf bank_mask:0xf
	v_fmac_f32_dpp v109, v157, v229 row_shr:1 row_mask:0xf bank_mask:0xf
	v_fmac_f32_dpp v110, v134, v242 row_shr:1 row_mask:0xf bank_mask:0xf
	v_fmac_f32_dpp v111, v135, v243 row_shr:1 row_mask:0xf bank_mask:0xf
	v_fmac_f32_dpp v112, v136, v244 row_shr:1 row_mask:0xf bank_mask:0xf
	v_fmac_f32_dpp v113, v137, v245 row_shr:1 row_mask:0xf bank_mask:0xf
	v_fmac_f32_dpp v106, v154, v230 row_shr:2 row_mask:0xf bank_mask:0xf
	v_fmac_f32_dpp v107, v155, v231 row_shr:2 row_mask:0xf bank_mask:0xf
	v_fmac_f32_dpp v108, v156, v232 row_shr:2 row_mask:0xf bank_mask:0xf
	v_fmac_f32_dpp v109, v157, v233 row_shr:2 row_mask:0xf bank_mask:0xf
	v_fmac_f32_dpp v110, v134, v246 row_shr:2 row_mask:0xf bank_mask:0xf
	v_fmac_f32_dpp v111, v135, v247 row_shr:2 row_mask:0xf bank_mask:0xf
	v_fmac_f32_dpp v112, v136, v248 row_shr:2 row_mask:0xf bank_mask:0xf
	v_fmac_f32_dpp v113, v137, v249 row_shr:2 row_mask:0xf bank_mask:0xf
	v_pk_mul_f32 v[114:115], v[106:107], v[106:107]
	v_pk_mul_f32 v[116:117], v[108:109], v[108:109]
	v_pk_fma_f32 v[114:115], v[114:115], v[132:133], v[196:197] op_sel_hi:[1,0,0]
	v_pk_fma_f32 v[116:117], v[116:117], v[132:133], v[196:197] op_sel_hi:[1,0,0]
	v_pk_mul_f32 v[114:115], v[106:107], v[114:115]
	v_pk_mul_f32 v[116:117], v[108:109], v[116:117]
	v_exp_f32_e32 v114, v114
	v_exp_f32_e32 v115, v115
	v_exp_f32_e32 v116, v116
	v_exp_f32_e32 v117, v117
	v_pk_add_f32 v[114:115], v[114:115], v[250:251] op_sel_hi:[1,0]
	v_pk_add_f32 v[116:117], v[116:117], v[250:251] op_sel_hi:[1,0]
	v_rcp_f32_e32 v114, v114
	v_rcp_f32_e32 v115, v115
	v_rcp_f32_e32 v116, v116
	v_rcp_f32_e32 v117, v117
	v_pk_mul_f32 v[114:115], v[106:107], v[114:115]
	v_pk_mul_f32 v[116:117], v[108:109], v[116:117]
	v_pk_mul_f32 v[114:115], v[110:111], v[114:115]
	v_pk_mul_f32 v[116:117], v[112:113], v[116:117]
	v_cvt_pk_bf16_f32 v114, v114, v115
	v_cvt_pk_bf16_f32 v115, v116, v117
	s_and_saveexec_b64 s[48:49], s[10:11]
	global_store_dwordx2 v199, v[114:115], s[68:69]
	s_or_b64 exec, exec, s[48:49]
	v_pk_mul_f32 v[150:151], v[150:151], v[190:191] op_sel_hi:[1,0]
	v_pk_mul_f32 v[152:153], v[152:153], v[190:191] op_sel_hi:[1,0]
	v_pk_mul_f32 v[146:147], v[146:147], v[190:191] op_sel_hi:[1,0]
	v_pk_mul_f32 v[148:149], v[148:149], v[190:191] op_sel_hi:[1,0]
	v_pk_fma_f32 v[118:119], v[150:151], v[218:219], v[222:223]
	v_pk_fma_f32 v[120:121], v[152:153], v[220:221], v[224:225]
	v_pk_fma_f32 v[122:123], v[146:147], v[234:235], v[238:239]
	v_pk_fma_f32 v[124:125], v[148:149], v[236:237], v[240:241]
	v_fmac_f32_dpp v118, v150, v226 row_shr:1 row_mask:0xf bank_mask:0xf
	v_fmac_f32_dpp v119, v151, v227 row_shr:1 row_mask:0xf bank_mask:0xf
	v_fmac_f32_dpp v120, v152, v228 row_shr:1 row_mask:0xf bank_mask:0xf
	v_fmac_f32_dpp v121, v153, v229 row_shr:1 row_mask:0xf bank_mask:0xf
	v_fmac_f32_dpp v122, v146, v242 row_shr:1 row_mask:0xf bank_mask:0xf
	v_fmac_f32_dpp v123, v147, v243 row_shr:1 row_mask:0xf bank_mask:0xf
	v_fmac_f32_dpp v124, v148, v244 row_shr:1 row_mask:0xf bank_mask:0xf
	v_fmac_f32_dpp v125, v149, v245 row_shr:1 row_mask:0xf bank_mask:0xf
	v_fmac_f32_dpp v118, v150, v230 row_shr:2 row_mask:0xf bank_mask:0xf
	v_fmac_f32_dpp v119, v151, v231 row_shr:2 row_mask:0xf bank_mask:0xf
	v_fmac_f32_dpp v120, v152, v232 row_shr:2 row_mask:0xf bank_mask:0xf
	v_fmac_f32_dpp v121, v153, v233 row_shr:2 row_mask:0xf bank_mask:0xf
	v_fmac_f32_dpp v122, v146, v246 row_shr:2 row_mask:0xf bank_mask:0xf
	v_fmac_f32_dpp v123, v147, v247 row_shr:2 row_mask:0xf bank_mask:0xf
	v_fmac_f32_dpp v124, v148, v248 row_shr:2 row_mask:0xf bank_mask:0xf
	v_fmac_f32_dpp v125, v149, v249 row_shr:2 row_mask:0xf bank_mask:0xf
	v_fmac_f32_dpp v118, v154, v226 row_shl:15 row_mask:0xf bank_mask:0xf
; __device__ __forceinline__ unsigned cvt_pk_bf16(float lo, float hi) { unsigned r; asm volatile("v_cvt_pk_bf16_f32 %0, %1, %2" : "=v"(r) : "v"(lo), "v"(hi)); return r; }
; __device__ __forceinline__ f32x4 gelu4(f32x4 v) { return (f32x4){gelu_t(v[0]), gelu_t(v[1]), gelu_t(v[2]), gelu_t(v[3])}; }
; template <int CTRL> __device__ __forceinline__ f32x4 dpp4(f32x4 v) { return (f32x4){dpp_f<CTRL>(v[0]), dpp_f<CTRL>(v[1]), dpp_f<CTRL>(v[2]), dpp_f<CTRL>(v[3])}; }
;     __device__ __forceinline__ void operator()(const f32x4 (&acc)[2][2][4][2], const Unit& u, int wr, int wc, int fr, int fq) const {
;     ...
;                     for (int m = 0; m < 4; ++m) {
;                         const f32x4 g = acc[ai][0][m][n] * rs[ai][m], v = acc[ai][1][m][n] * rs[ai][m];
;                         const f32x4 g1 = dpp4<0x121>(g), g2 = dpp4<0x122>(g), v1 = dpp4<0x121>(v), v2 = dpp4<0x122>(v);
;                         const f32x4 gp1 = (fr >= 1) ? g1 : pg1, gp2 = (fr >= 2) ? g2 : pg2, vp1 = (fr >= 1) ? v1 : pv1, vp2 = (fr >= 2) ? v2 : pv2;
;                         const f32x4 cgt = bg + wg0 * g + wg1 * gp1 + wg2 * gp2, cvl = bv + wv0 * v + wv1 * vp1 + wv2 * vp2;
;                         const f32x4 o = gelu4(cgt) * cvl;
;                         typedef unsigned u32x2e __attribute__((ext_vector_type(2)));
;                         u32x2e w; w.x = cvt_pk_bf16(o[0], o[1]); w.y = cvt_pk_bf16(o[2], o[3]);
;                         if (!(m == 0 && fr < 2)) *(u32x2e*)((bf16_t*)O + (size_t)(row0 + ai * HALF + m * 16) * DFFc + c) = w;
	v_fmac_f32_dpp v119, v155, v227 row_shl:15 row_mask:0xf bank_mask:0xf
	v_fmac_f32_dpp v120, v156, v228 row_shl:15 row_mask:0xf bank_mask:0xf
	v_fmac_f32_dpp v121, v157, v229 row_shl:15 row_mask:0xf bank_mask:0xf
	v_fmac_f32_dpp v122, v134, v242 row_shl:15 row_mask:0xf bank_mask:0xf
	v_fmac_f32_dpp v123, v135, v243 row_shl:15 row_mask:0xf bank_mask:0xf
	v_fmac_f32_dpp v124, v136, v244 row_shl:15 row_mask:0xf bank_mask:0xf
	v_fmac_f32_dpp v125, v137, v245 row_shl:15 row_mask:0xf bank_mask:0xf
	v_fmac_f32_dpp v118, v154, v230 row_shl:14 row_mask:0xf bank_mask:0xf
	v_fmac_f32_dpp v119, v155, v231 row_shl:14 row_mask:0xf bank_mask:0xf
	v_fmac_f32_dpp v120, v156, v232 row_shl:14 row_mask:0xf bank_mask:0xf
	v_fmac_f32_dpp v121, v157, v233 row_shl:14 row_mask:0xf bank_mask:0xf
	v_fmac_f32_dpp v122, v134, v246 row_shl:14 row_mask:0xf bank_mask:0xf
	v_fmac_f32_dpp v123, v135, v247 row_shl:14 row_mask:0xf bank_mask:0xf
	v_fmac_f32_dpp v124, v136, v248 row_shl:14 row_mask:0xf bank_mask:0xf
	v_fmac_f32_dpp v125, v137, v249 row_shl:14 row_mask:0xf bank_mask:0xf
	v_pk_mul_f32 v[126:127], v[118:119], v[118:119]
	v_pk_mul_f32 v[128:129], v[120:121], v[120:121]
	v_pk_fma_f32 v[126:127], v[126:127], v[132:133], v[196:197] op_sel_hi:[1,0,0]
	v_pk_fma_f32 v[128:129], v[128:129], v[132:133], v[196:197] op_sel_hi:[1,0,0]
	v_pk_mul_f32 v[126:127], v[118:119], v[126:127]
	v_pk_mul_f32 v[128:129], v[120:121], v[128:129]
	v_exp_f32_e32 v126, v126
	v_exp_f32_e32 v127, v127
	v_exp_f32_e32 v128, v128
	v_exp_f32_e32 v129, v129
	v_pk_add_f32 v[126:127], v[126:127], v[250:251] op_sel_hi:[1,0]
	v_pk_add_f32 v[128:129], v[128:129], v[250:251] op_sel_hi:[1,0]
	v_rcp_f32_e32 v126, v126
	v_rcp_f32_e32 v127, v127
	v_rcp_f32_e32 v128, v128
	v_rcp_f32_e32 v129, v129
	v_pk_mul_f32 v[126:127], v[118:119], v[126:127]
	v_pk_mul_f32 v[128:129], v[120:121], v[128:129]
	v_pk_mul_f32 v[126:127], v[122:123], v[126:127]
	v_pk_mul_f32 v[128:129], v[124:125], v[128:129]
	v_cvt_pk_bf16_f32 v126, v126, v127
	v_cvt_pk_bf16_f32 v127, v128, v129
	v_add_u32_e32 v131, 0x2c000, v199
	global_store_dwordx2 v131, v[126:127], s[68:69]
	v_pk_mul_f32 v[142:143], v[142:143], v[192:193] op_sel_hi:[1,0]
	v_pk_mul_f32 v[144:145], v[144:145], v[192:193] op_sel_hi:[1,0]
	v_pk_mul_f32 v[138:139], v[138:139], v[192:193] op_sel_hi:[1,0]
	v_pk_mul_f32 v[140:141], v[140:141], v[192:193] op_sel_hi:[1,0]
	v_pk_fma_f32 v[106:107], v[142:143], v[218:219], v[222:223]
	v_pk_fma_f32 v[108:109], v[144:145], v[220:221], v[224:225]
	v_pk_fma_f32 v[110:111], v[138:139], v[234:235], v[238:239]
	v_pk_fma_f32 v[112:113], v[140:141], v[236:237], v[240:241]
	v_fmac_f32_dpp v106, v142, v226 row_shr:1 row_mask:0xf bank_mask:0xf
	v_fmac_f32_dpp v107, v143, v227 row_shr:1 row_mask:0xf bank_mask:0xf
	v_fmac_f32_dpp v108, v144, v228 row_shr:1 row_mask:0xf bank_mask:0xf
	v_fmac_f32_dpp v109, v145, v229 row_shr:1 row_mask:0xf bank_mask:0xf
	v_fmac_f32_dpp v110, v138, v242 row_shr:1 row_mask:0xf bank_mask:0xf
	v_fmac_f32_dpp v111, v139, v243 row_shr:1 row_mask:0xf bank_mask:0xf
	v_fmac_f32_dpp v112, v140, v244 row_shr:1 row_mask:0xf bank_mask:0xf
	v_fmac_f32_dpp v113, v141, v245 row_shr:1 row_mask:0xf bank_mask:0xf
	v_fmac_f32_dpp v106, v142, v230 row_shr:2 row_mask:0xf bank_mask:0xf
	v_fmac_f32_dpp v107, v143, v231 row_shr:2 row_mask:0xf bank_mask:0xf
	v_fmac_f32_dpp v108, v144, v232 row_shr:2 row_mask:0xf bank_mask:0xf
	v_fmac_f32_dpp v109, v145, v233 row_shr:2 row_mask:0xf bank_mask:0xf
	v_fmac_f32_dpp v110, v138, v246 row_shr:2 row_mask:0xf bank_mask:0xf
	v_fmac_f32_dpp v111, v139, v247 row_shr:2 row_mask:0xf bank_mask:0xf
	v_fmac_f32_dpp v112, v140, v248 row_shr:2 row_mask:0xf bank_mask:0xf
	v_fmac_f32_dpp v113, v141, v249 row_shr:2 row_mask:0xf bank_mask:0xf
	v_fmac_f32_dpp v106, v150, v226 row_shl:15 row_mask:0xf bank_mask:0xf
	v_fmac_f32_dpp v107, v151, v227 row_shl:15 row_mask:0xf bank_mask:0xf
	v_fmac_f32_dpp v108, v152, v228 row_shl:15 row_mask:0xf bank_mask:0xf
	v_fmac_f32_dpp v109, v153, v229 row_shl:15 row_mask:0xf bank_mask:0xf
	v_fmac_f32_dpp v110, v146, v242 row_shl:15 row_mask:0xf bank_mask:0xf
	v_fmac_f32_dpp v111, v147, v243 row_shl:15 row_mask:0xf bank_mask:0xf
	v_fmac_f32_dpp v112, v148, v244 row_shl:15 row_mask:0xf bank_mask:0xf
	v_fmac_f32_dpp v113, v149, v245 row_shl:15 row_mask:0xf bank_mask:0xf
	v_fmac_f32_dpp v106, v150, v230 row_shl:14 row_mask:0xf bank_mask:0xf
	v_fmac_f32_dpp v107, v151, v231 row_shl:14 row_mask:0xf bank_mask:0xf
	v_fmac_f32_dpp v108, v152, v232 row_shl:14 row_mask:0xf bank_mask:0xf
	v_fmac_f32_dpp v109, v153, v233 row_shl:14 row_mask:0xf bank_mask:0xf
	v_fmac_f32_dpp v110, v146, v246 row_shl:14 row_mask:0xf bank_mask:0xf
	v_fmac_f32_dpp v111, v147, v247 row_shl:14 row_mask:0xf bank_mask:0xf
	v_fmac_f32_dpp v112, v148, v248 row_shl:14 row_mask:0xf bank_mask:0xf
	v_fmac_f32_dpp v113, v149, v249 row_shl:14 row_mask:0xf bank_mask:0xf
	v_pk_mul_f32 v[114:115], v[106:107], v[106:107]
	v_pk_mul_f32 v[116:117], v[108:109], v[108:109]
	v_pk_fma_f32 v[114:115], v[114:115], v[132:133], v[196:197] op_sel_hi:[1,0,0]
	v_pk_fma_f32 v[116:117], v[116:117], v[132:133], v[196:197] op_sel_hi:[1,0,0]
	v_pk_mul_f32 v[114:115], v[106:107], v[114:115]
	v_pk_mul_f32 v[116:117], v[108:109], v[116:117]
	v_exp_f32_e32 v114, v114
	v_exp_f32_e32 v115, v115
	v_exp_f32_e32 v116, v116
	v_exp_f32_e32 v117, v117
	v_pk_add_f32 v[114:115], v[114:115], v[250:251] op_sel_hi:[1,0]
	v_pk_add_f32 v[116:117], v[116:117], v[250:251] op_sel_hi:[1,0]
	v_rcp_f32_e32 v114, v114
	v_rcp_f32_e32 v115, v115
	v_rcp_f32_e32 v116, v116
	v_rcp_f32_e32 v117, v117
	v_pk_mul_f32 v[114:115], v[106:107], v[114:115]
	v_pk_mul_f32 v[116:117], v[108:109], v[116:117]
; __device__ __forceinline__ unsigned cvt_pk_bf16(float lo, float hi) { unsigned r; asm volatile("v_cvt_pk_bf16_f32 %0, %1, %2" : "=v"(r) : "v"(lo), "v"(hi)); return r; }
; __device__ __forceinline__ f32x4 gelu4(f32x4 v) { return (f32x4){gelu_t(v[0]), gelu_t(v[1]), gelu_t(v[2]), gelu_t(v[3])}; }
; template <int CTRL> __device__ __forceinline__ f32x4 dpp4(f32x4 v) { return (f32x4){dpp_f<CTRL>(v[0]), dpp_f<CTRL>(v[1]), dpp_f<CTRL>(v[2]), dpp_f<CTRL>(v[3])}; }
;     __device__ __forceinline__ void operator()(const f32x4 (&acc)[2][2][4][2], const Unit& u, int wr, int wc, int fr, int fq) const {
;     ...
;                 const f32x4 wg0 = *(const f32x4*)(bias + c), wg1 = *(const f32x4*)(bias + NUPc + c), wg2 = *(const f32x4*)(bias + 2 * NUPc + c), bg = *(const f32x4*)(xin + c);
;                 const f32x4 wv0 = *(const f32x4*)(bias + DFFc + c), wv1 = *(const f32x4*)(bias + NUPc + DFFc + c), wv2 = *(const f32x4*)(bias + 2 * NUPc + DFFc + c), bv = *(const f32x4*)(xin + DFFc + c);
; #pragma unroll
;                 for (int ai = 0; ai < 2; ++ai) {
;                     f32x4 pg1 = (f32x4){0.f, 0.f, 0.f, 0.f}, pg2 = pg1, pv1 = pg1, pv2 = pg1;
; #pragma unroll
;                     for (int m = 0; m < 4; ++m) {
;                         const f32x4 g = acc[ai][0][m][n] * rs[ai][m], v = acc[ai][1][m][n] * rs[ai][m];
;                         const f32x4 g1 = dpp4<0x121>(g), g2 = dpp4<0x122>(g), v1 = dpp4<0x121>(v), v2 = dpp4<0x122>(v);
;                         const f32x4 gp1 = (fr >= 1) ? g1 : pg1, gp2 = (fr >= 2) ? g2 : pg2, vp1 = (fr >= 1) ? v1 : pv1, vp2 = (fr >= 2) ? v2 : pv2;
;                         const f32x4 cgt = bg + wg0 * g + wg1 * gp1 + wg2 * gp2, cvl = bv + wv0 * v + wv1 * vp1 + wv2 * vp2;
;                         const f32x4 o = gelu4(cgt) * cvl;
;                         typedef unsigned u32x2e __attribute__((ext_vector_type(2)));
;                         u32x2e w; w.x = cvt_pk_bf16(o[0], o[1]); w.y = cvt_pk_bf16(o[2], o[3]);
;                         if (!(m == 0 && fr < 2)) *(u32x2e*)((bf16_t*)O + (size_t)(row0 + ai * HALF + m * 16) * DFFc + c) = w;
	v_pk_mul_f32 v[114:115], v[110:111], v[114:115]
	v_pk_mul_f32 v[116:117], v[112:113], v[116:117]
	v_cvt_pk_bf16_f32 v114, v114, v115
	v_cvt_pk_bf16_f32 v115, v116, v117
	v_add_u32_e32 v130, 0x58000, v199
	global_store_dwordx2 v130, v[114:115], s[68:69]
	v_pk_mul_f32 v[102:103], v[102:103], v[184:185] op_sel_hi:[1,0]
	v_pk_mul_f32 v[104:105], v[104:105], v[184:185] op_sel_hi:[1,0]
	v_pk_mul_f32 v[98:99], v[98:99], v[184:185] op_sel_hi:[1,0]
	v_pk_mul_f32 v[100:101], v[100:101], v[184:185] op_sel_hi:[1,0]
	v_pk_fma_f32 v[118:119], v[102:103], v[218:219], v[222:223]
	v_pk_fma_f32 v[120:121], v[104:105], v[220:221], v[224:225]
	v_pk_fma_f32 v[122:123], v[98:99], v[234:235], v[238:239]
	v_pk_fma_f32 v[124:125], v[100:101], v[236:237], v[240:241]
	v_fmac_f32_dpp v118, v102, v226 row_shr:1 row_mask:0xf bank_mask:0xf
	v_fmac_f32_dpp v119, v103, v227 row_shr:1 row_mask:0xf bank_mask:0xf
	v_fmac_f32_dpp v120, v104, v228 row_shr:1 row_mask:0xf bank_mask:0xf
	v_fmac_f32_dpp v121, v105, v229 row_shr:1 row_mask:0xf bank_mask:0xf
	v_fmac_f32_dpp v122, v98, v242 row_shr:1 row_mask:0xf bank_mask:0xf
	v_fmac_f32_dpp v123, v99, v243 row_shr:1 row_mask:0xf bank_mask:0xf
	v_fmac_f32_dpp v124, v100, v244 row_shr:1 row_mask:0xf bank_mask:0xf
	v_fmac_f32_dpp v125, v101, v245 row_shr:1 row_mask:0xf bank_mask:0xf
	v_fmac_f32_dpp v118, v102, v230 row_shr:2 row_mask:0xf bank_mask:0xf
	v_fmac_f32_dpp v119, v103, v231 row_shr:2 row_mask:0xf bank_mask:0xf
	v_fmac_f32_dpp v120, v104, v232 row_shr:2 row_mask:0xf bank_mask:0xf
	v_fmac_f32_dpp v121, v105, v233 row_shr:2 row_mask:0xf bank_mask:0xf
	v_fmac_f32_dpp v122, v98, v246 row_shr:2 row_mask:0xf bank_mask:0xf
	v_fmac_f32_dpp v123, v99, v247 row_shr:2 row_mask:0xf bank_mask:0xf
	v_fmac_f32_dpp v124, v100, v248 row_shr:2 row_mask:0xf bank_mask:0xf
	v_fmac_f32_dpp v125, v101, v249 row_shr:2 row_mask:0xf bank_mask:0xf
	v_fmac_f32_dpp v118, v142, v226 row_shl:15 row_mask:0xf bank_mask:0xf
	v_fmac_f32_dpp v119, v143, v227 row_shl:15 row_mask:0xf bank_mask:0xf
	v_fmac_f32_dpp v120, v144, v228 row_shl:15 row_mask:0xf bank_mask:0xf
	v_fmac_f32_dpp v121, v145, v229 row_shl:15 row_mask:0xf bank_mask:0xf
	v_fmac_f32_dpp v122, v138, v242 row_shl:15 row_mask:0xf bank_mask:0xf
	v_fmac_f32_dpp v123, v139, v243 row_shl:15 row_mask:0xf bank_mask:0xf
	v_fmac_f32_dpp v124, v140, v244 row_shl:15 row_mask:0xf bank_mask:0xf
	v_fmac_f32_dpp v125, v141, v245 row_shl:15 row_mask:0xf bank_mask:0xf
	v_fmac_f32_dpp v118, v142, v230 row_shl:14 row_mask:0xf bank_mask:0xf
	v_fmac_f32_dpp v119, v143, v231 row_shl:14 row_mask:0xf bank_mask:0xf
	v_fmac_f32_dpp v120, v144, v232 row_shl:14 row_mask:0xf bank_mask:0xf
	v_fmac_f32_dpp v121, v145, v233 row_shl:14 row_mask:0xf bank_mask:0xf
	v_fmac_f32_dpp v122, v138, v246 row_shl:14 row_mask:0xf bank_mask:0xf
	v_fmac_f32_dpp v123, v139, v247 row_shl:14 row_mask:0xf bank_mask:0xf
	v_fmac_f32_dpp v124, v140, v248 row_shl:14 row_mask:0xf bank_mask:0xf
	v_fmac_f32_dpp v125, v141, v249 row_shl:14 row_mask:0xf bank_mask:0xf
	v_pk_mul_f32 v[126:127], v[118:119], v[118:119]
	v_pk_mul_f32 v[128:129], v[120:121], v[120:121]
	v_pk_fma_f32 v[126:127], v[126:127], v[132:133], v[196:197] op_sel_hi:[1,0,0]
	v_pk_fma_f32 v[128:129], v[128:129], v[132:133], v[196:197] op_sel_hi:[1,0,0]
	v_pk_mul_f32 v[126:127], v[118:119], v[126:127]
	v_pk_mul_f32 v[128:129], v[120:121], v[128:129]
	v_exp_f32_e32 v126, v126
	v_exp_f32_e32 v127, v127
	v_exp_f32_e32 v128, v128
	v_exp_f32_e32 v129, v129
	v_pk_add_f32 v[126:127], v[126:127], v[250:251] op_sel_hi:[1,0]
	v_pk_add_f32 v[128:129], v[128:129], v[250:251] op_sel_hi:[1,0]
	v_rcp_f32_e32 v126, v126
	v_rcp_f32_e32 v127, v127
	v_rcp_f32_e32 v128, v128
	v_rcp_f32_e32 v129, v129
	v_pk_mul_f32 v[126:127], v[118:119], v[126:127]
	v_pk_mul_f32 v[128:129], v[120:121], v[128:129]
	v_pk_mul_f32 v[126:127], v[122:123], v[126:127]
	v_pk_mul_f32 v[128:129], v[124:125], v[128:129]
	v_cvt_pk_bf16_f32 v126, v126, v127
	v_cvt_pk_bf16_f32 v127, v128, v129
	v_add_u32_e32 v131, 0x84000, v199
	global_store_dwordx2 v131, v[126:127], s[68:69]
	global_load_dwordx4 v[154:157], v205, s[18:19] offset:16
	global_load_dwordx4 v[150:153], v205, s[20:21] offset:16
	global_load_dwordx4 v[142:145], v205, s[26:27] offset:16
	global_load_dwordx4 v[102:105], v205, s[28:29] offset:16
	global_load_dwordx4 v[134:137], v205, s[30:31] offset:16
	global_load_dwordx4 v[146:149], v205, s[38:39] offset:16
	global_load_dwordx4 v[138:141], v205, s[34:35] offset:16
	global_load_dwordx4 v[98:101], v205, s[36:37] offset:16
	v_pk_mul_f32 v[94:95], v[94:95], v[182:183] op_sel_hi:[1,0]
	v_pk_mul_f32 v[96:97], v[96:97], v[182:183] op_sel_hi:[1,0]
	v_pk_mul_f32 v[90:91], v[90:91], v[182:183] op_sel_hi:[1,0]
	v_pk_mul_f32 v[92:93], v[92:93], v[182:183] op_sel_hi:[1,0]
	v_pk_fma_f32 v[106:107], v[94:95], v[218:219], v[222:223]
	v_pk_fma_f32 v[108:109], v[96:97], v[220:221], v[224:225]
	v_pk_fma_f32 v[110:111], v[90:91], v[234:235], v[238:239]
	v_pk_fma_f32 v[112:113], v[92:93], v[236:237], v[240:241]
	v_fmac_f32_dpp v106, v94, v226 row_shr:1 row_mask:0xf bank_mask:0xf
	v_fmac_f32_dpp v107, v95, v227 row_shr:1 row_mask:0xf bank_mask:0xf
	v_fmac_f32_dpp v108, v96, v228 row_shr:1 row_mask:0xf bank_mask:0xf
	v_fmac_f32_dpp v109, v97, v229 row_shr:1 row_mask:0xf bank_mask:0xf
	v_fmac_f32_dpp v110, v90, v242 row_shr:1 row_mask:0xf bank_mask:0xf
	v_fmac_f32_dpp v111, v91, v243 row_shr:1 row_mask:0xf bank_mask:0xf
	v_fmac_f32_dpp v112, v92, v244 row_shr:1 row_mask:0xf bank_mask:0xf
	v_fmac_f32_dpp v113, v93, v245 row_shr:1 row_mask:0xf bank_mask:0xf
	v_fmac_f32_dpp v106, v94, v230 row_shr:2 row_mask:0xf bank_mask:0xf
; __device__ __forceinline__ unsigned cvt_pk_bf16(float lo, float hi) { unsigned r; asm volatile("v_cvt_pk_bf16_f32 %0, %1, %2" : "=v"(r) : "v"(lo), "v"(hi)); return r; }
; __device__ __forceinline__ f32x4 gelu4(f32x4 v) { return (f32x4){gelu_t(v[0]), gelu_t(v[1]), gelu_t(v[2]), gelu_t(v[3])}; }
; template <int CTRL> __device__ __forceinline__ f32x4 dpp4(f32x4 v) { return (f32x4){dpp_f<CTRL>(v[0]), dpp_f<CTRL>(v[1]), dpp_f<CTRL>(v[2]), dpp_f<CTRL>(v[3])}; }
;     __device__ __forceinline__ void operator()(const f32x4 (&acc)[2][2][4][2], const Unit& u, int wr, int wc, int fr, int fq) const {
;     ...
;                     for (int m = 0; m < 4; ++m) {
;                         const f32x4 g = acc[ai][0][m][n] * rs[ai][m], v = acc[ai][1][m][n] * rs[ai][m];
;                         const f32x4 g1 = dpp4<0x121>(g), g2 = dpp4<0x122>(g), v1 = dpp4<0x121>(v), v2 = dpp4<0x122>(v);
;                         const f32x4 gp1 = (fr >= 1) ? g1 : pg1, gp2 = (fr >= 2) ? g2 : pg2, vp1 = (fr >= 1) ? v1 : pv1, vp2 = (fr >= 2) ? v2 : pv2;
;                         const f32x4 cgt = bg + wg0 * g + wg1 * gp1 + wg2 * gp2, cvl = bv + wv0 * v + wv1 * vp1 + wv2 * vp2;
;                         const f32x4 o = gelu4(cgt) * cvl;
;                         typedef unsigned u32x2e __attribute__((ext_vector_type(2)));
;                         u32x2e w; w.x = cvt_pk_bf16(o[0], o[1]); w.y = cvt_pk_bf16(o[2], o[3]);
;                         if (!(m == 0 && fr < 2)) *(u32x2e*)((bf16_t*)O + (size_t)(row0 + ai * HALF + m * 16) * DFFc + c) = w;
	v_fmac_f32_dpp v107, v95, v231 row_shr:2 row_mask:0xf bank_mask:0xf
	v_fmac_f32_dpp v108, v96, v232 row_shr:2 row_mask:0xf bank_mask:0xf
	v_fmac_f32_dpp v109, v97, v233 row_shr:2 row_mask:0xf bank_mask:0xf
	v_fmac_f32_dpp v110, v90, v246 row_shr:2 row_mask:0xf bank_mask:0xf
	v_fmac_f32_dpp v111, v91, v247 row_shr:2 row_mask:0xf bank_mask:0xf
	v_fmac_f32_dpp v112, v92, v248 row_shr:2 row_mask:0xf bank_mask:0xf
	v_fmac_f32_dpp v113, v93, v249 row_shr:2 row_mask:0xf bank_mask:0xf
	v_pk_mul_f32 v[114:115], v[106:107], v[106:107]
	v_pk_mul_f32 v[116:117], v[108:109], v[108:109]
	v_pk_fma_f32 v[114:115], v[114:115], v[132:133], v[196:197] op_sel_hi:[1,0,0]
	v_pk_fma_f32 v[116:117], v[116:117], v[132:133], v[196:197] op_sel_hi:[1,0,0]
	v_pk_mul_f32 v[114:115], v[106:107], v[114:115]
	v_pk_mul_f32 v[116:117], v[108:109], v[116:117]
	v_exp_f32_e32 v114, v114
	v_exp_f32_e32 v115, v115
	v_exp_f32_e32 v116, v116
	v_exp_f32_e32 v117, v117
	v_pk_add_f32 v[114:115], v[114:115], v[250:251] op_sel_hi:[1,0]
	v_pk_add_f32 v[116:117], v[116:117], v[250:251] op_sel_hi:[1,0]
	v_rcp_f32_e32 v114, v114
	v_rcp_f32_e32 v115, v115
	v_rcp_f32_e32 v116, v116
	v_rcp_f32_e32 v117, v117
	v_pk_mul_f32 v[114:115], v[106:107], v[114:115]
	v_pk_mul_f32 v[116:117], v[108:109], v[116:117]
	v_pk_mul_f32 v[114:115], v[110:111], v[114:115]
	v_pk_mul_f32 v[116:117], v[112:113], v[116:117]
	v_cvt_pk_bf16_f32 v114, v114, v115
	v_cvt_pk_bf16_f32 v115, v116, v117
	v_add_u32_e32 v130, 0x160000, v199
	s_and_saveexec_b64 s[48:49], s[10:11]
	global_store_dwordx2 v130, v[114:115], s[68:69]
	s_or_b64 exec, exec, s[48:49]
	v_pk_mul_f32 v[86:87], v[86:87], v[180:181] op_sel_hi:[1,0]
	v_pk_mul_f32 v[88:89], v[88:89], v[180:181] op_sel_hi:[1,0]
	v_pk_mul_f32 v[82:83], v[82:83], v[180:181] op_sel_hi:[1,0]
	v_pk_mul_f32 v[84:85], v[84:85], v[180:181] op_sel_hi:[1,0]
	v_pk_fma_f32 v[118:119], v[86:87], v[218:219], v[222:223]
	v_pk_fma_f32 v[120:121], v[88:89], v[220:221], v[224:225]
	v_pk_fma_f32 v[122:123], v[82:83], v[234:235], v[238:239]
	v_pk_fma_f32 v[124:125], v[84:85], v[236:237], v[240:241]
	v_fmac_f32_dpp v118, v86, v226 row_shr:1 row_mask:0xf bank_mask:0xf
	v_fmac_f32_dpp v119, v87, v227 row_shr:1 row_mask:0xf bank_mask:0xf
	v_fmac_f32_dpp v120, v88, v228 row_shr:1 row_mask:0xf bank_mask:0xf
	v_fmac_f32_dpp v121, v89, v229 row_shr:1 row_mask:0xf bank_mask:0xf
	v_fmac_f32_dpp v122, v82, v242 row_shr:1 row_mask:0xf bank_mask:0xf
	v_fmac_f32_dpp v123, v83, v243 row_shr:1 row_mask:0xf bank_mask:0xf
	v_fmac_f32_dpp v124, v84, v244 row_shr:1 row_mask:0xf bank_mask:0xf
	v_fmac_f32_dpp v125, v85, v245 row_shr:1 row_mask:0xf bank_mask:0xf
	v_fmac_f32_dpp v118, v86, v230 row_shr:2 row_mask:0xf bank_mask:0xf
	v_fmac_f32_dpp v119, v87, v231 row_shr:2 row_mask:0xf bank_mask:0xf
	v_fmac_f32_dpp v120, v88, v232 row_shr:2 row_mask:0xf bank_mask:0xf
	v_fmac_f32_dpp v121, v89, v233 row_shr:2 row_mask:0xf bank_mask:0xf
	v_fmac_f32_dpp v122, v82, v246 row_shr:2 row_mask:0xf bank_mask:0xf
	v_fmac_f32_dpp v123, v83, v247 row_shr:2 row_mask:0xf bank_mask:0xf
	v_fmac_f32_dpp v124, v84, v248 row_shr:2 row_mask:0xf bank_mask:0xf
	v_fmac_f32_dpp v125, v85, v249 row_shr:2 row_mask:0xf bank_mask:0xf
	v_fmac_f32_dpp v118, v94, v226 row_shl:15 row_mask:0xf bank_mask:0xf
	v_fmac_f32_dpp v119, v95, v227 row_shl:15 row_mask:0xf bank_mask:0xf
	v_fmac_f32_dpp v120, v96, v228 row_shl:15 row_mask:0xf bank_mask:0xf
	v_fmac_f32_dpp v121, v97, v229 row_shl:15 row_mask:0xf bank_mask:0xf
	v_fmac_f32_dpp v122, v90, v242 row_shl:15 row_mask:0xf bank_mask:0xf
	v_fmac_f32_dpp v123, v91, v243 row_shl:15 row_mask:0xf bank_mask:0xf
	v_fmac_f32_dpp v124, v92, v244 row_shl:15 row_mask:0xf bank_mask:0xf
	v_fmac_f32_dpp v125, v93, v245 row_shl:15 row_mask:0xf bank_mask:0xf
	v_fmac_f32_dpp v118, v94, v230 row_shl:14 row_mask:0xf bank_mask:0xf
	v_fmac_f32_dpp v119, v95, v231 row_shl:14 row_mask:0xf bank_mask:0xf
	v_fmac_f32_dpp v120, v96, v232 row_shl:14 row_mask:0xf bank_mask:0xf
	v_fmac_f32_dpp v121, v97, v233 row_shl:14 row_mask:0xf bank_mask:0xf
	v_fmac_f32_dpp v122, v90, v246 row_shl:14 row_mask:0xf bank_mask:0xf
	v_fmac_f32_dpp v123, v91, v247 row_shl:14 row_mask:0xf bank_mask:0xf
	v_fmac_f32_dpp v124, v92, v248 row_shl:14 row_mask:0xf bank_mask:0xf
	v_fmac_f32_dpp v125, v93, v249 row_shl:14 row_mask:0xf bank_mask:0xf
	v_pk_mul_f32 v[126:127], v[118:119], v[118:119]
	v_pk_mul_f32 v[128:129], v[120:121], v[120:121]
	v_pk_fma_f32 v[126:127], v[126:127], v[132:133], v[196:197] op_sel_hi:[1,0,0]
	v_pk_fma_f32 v[128:129], v[128:129], v[132:133], v[196:197] op_sel_hi:[1,0,0]
	v_pk_mul_f32 v[126:127], v[118:119], v[126:127]
	v_pk_mul_f32 v[128:129], v[120:121], v[128:129]
	v_exp_f32_e32 v126, v126
	v_exp_f32_e32 v127, v127
	v_exp_f32_e32 v128, v128
	v_exp_f32_e32 v129, v129
	v_pk_add_f32 v[126:127], v[126:127], v[250:251] op_sel_hi:[1,0]
	v_pk_add_f32 v[128:129], v[128:129], v[250:251] op_sel_hi:[1,0]
	v_rcp_f32_e32 v126, v126
	v_rcp_f32_e32 v127, v127
	v_rcp_f32_e32 v128, v128
	v_rcp_f32_e32 v129, v129
	v_pk_mul_f32 v[126:127], v[118:119], v[126:127]
	v_pk_mul_f32 v[128:129], v[120:121], v[128:129]
	v_pk_mul_f32 v[126:127], v[122:123], v[126:127]
	v_pk_mul_f32 v[128:129], v[124:125], v[128:129]
	v_cvt_pk_bf16_f32 v126, v126, v127
	v_cvt_pk_bf16_f32 v127, v128, v129
	v_add_u32_e32 v131, 0x18c000, v199
	global_store_dwordx2 v131, v[126:127], s[68:69]
	v_pk_mul_f32 v[78:79], v[78:79], v[200:201] op_sel_hi:[1,0]
	v_pk_mul_f32 v[80:81], v[80:81], v[200:201] op_sel_hi:[1,0]
	v_pk_mul_f32 v[74:75], v[74:75], v[200:201] op_sel_hi:[1,0]
	v_pk_mul_f32 v[76:77], v[76:77], v[200:201] op_sel_hi:[1,0]
	v_pk_fma_f32 v[106:107], v[78:79], v[218:219], v[222:223]
; __device__ __forceinline__ unsigned cvt_pk_bf16(float lo, float hi) { unsigned r; asm volatile("v_cvt_pk_bf16_f32 %0, %1, %2" : "=v"(r) : "v"(lo), "v"(hi)); return r; }
; __device__ __forceinline__ f32x4 gelu4(f32x4 v) { return (f32x4){gelu_t(v[0]), gelu_t(v[1]), gelu_t(v[2]), gelu_t(v[3])}; }
; template <int CTRL> __device__ __forceinline__ f32x4 dpp4(f32x4 v) { return (f32x4){dpp_f<CTRL>(v[0]), dpp_f<CTRL>(v[1]), dpp_f<CTRL>(v[2]), dpp_f<CTRL>(v[3])}; }
;     __device__ __forceinline__ void operator()(const f32x4 (&acc)[2][2][4][2], const Unit& u, int wr, int wc, int fr, int fq) const {
;     ...
;                     for (int m = 0; m < 4; ++m) {
;                         const f32x4 g = acc[ai][0][m][n] * rs[ai][m], v = acc[ai][1][m][n] * rs[ai][m];
;                         const f32x4 g1 = dpp4<0x121>(g), g2 = dpp4<0x122>(g), v1 = dpp4<0x121>(v), v2 = dpp4<0x122>(v);
;                         const f32x4 gp1 = (fr >= 1) ? g1 : pg1, gp2 = (fr >= 2) ? g2 : pg2, vp1 = (fr >= 1) ? v1 : pv1, vp2 = (fr >= 2) ? v2 : pv2;
;                         const f32x4 cgt = bg + wg0 * g + wg1 * gp1 + wg2 * gp2, cvl = bv + wv0 * v + wv1 * vp1 + wv2 * vp2;
;                         const f32x4 o = gelu4(cgt) * cvl;
;                         typedef unsigned u32x2e __attribute__((ext_vector_type(2)));
;                         u32x2e w; w.x = cvt_pk_bf16(o[0], o[1]); w.y = cvt_pk_bf16(o[2], o[3]);
;                         if (!(m == 0 && fr < 2)) *(u32x2e*)((bf16_t*)O + (size_t)(row0 + ai * HALF + m * 16) * DFFc + c) = w;
	v_pk_fma_f32 v[108:109], v[80:81], v[220:221], v[224:225]
	v_pk_fma_f32 v[110:111], v[74:75], v[234:235], v[238:239]
	v_pk_fma_f32 v[112:113], v[76:77], v[236:237], v[240:241]
	v_fmac_f32_dpp v106, v78, v226 row_shr:1 row_mask:0xf bank_mask:0xf
	v_fmac_f32_dpp v107, v79, v227 row_shr:1 row_mask:0xf bank_mask:0xf
	v_fmac_f32_dpp v108, v80, v228 row_shr:1 row_mask:0xf bank_mask:0xf
	v_fmac_f32_dpp v109, v81, v229 row_shr:1 row_mask:0xf bank_mask:0xf
	v_fmac_f32_dpp v110, v74, v242 row_shr:1 row_mask:0xf bank_mask:0xf
	v_fmac_f32_dpp v111, v75, v243 row_shr:1 row_mask:0xf bank_mask:0xf
	v_fmac_f32_dpp v112, v76, v244 row_shr:1 row_mask:0xf bank_mask:0xf
	v_fmac_f32_dpp v113, v77, v245 row_shr:1 row_mask:0xf bank_mask:0xf
	v_fmac_f32_dpp v106, v78, v230 row_shr:2 row_mask:0xf bank_mask:0xf
	v_fmac_f32_dpp v107, v79, v231 row_shr:2 row_mask:0xf bank_mask:0xf
	v_fmac_f32_dpp v108, v80, v232 row_shr:2 row_mask:0xf bank_mask:0xf
	v_fmac_f32_dpp v109, v81, v233 row_shr:2 row_mask:0xf bank_mask:0xf
	v_fmac_f32_dpp v110, v74, v246 row_shr:2 row_mask:0xf bank_mask:0xf
	v_fmac_f32_dpp v111, v75, v247 row_shr:2 row_mask:0xf bank_mask:0xf
	v_fmac_f32_dpp v112, v76, v248 row_shr:2 row_mask:0xf bank_mask:0xf
	v_fmac_f32_dpp v113, v77, v249 row_shr:2 row_mask:0xf bank_mask:0xf
	v_fmac_f32_dpp v106, v86, v226 row_shl:15 row_mask:0xf bank_mask:0xf
	v_fmac_f32_dpp v107, v87, v227 row_shl:15 row_mask:0xf bank_mask:0xf
	v_fmac_f32_dpp v108, v88, v228 row_shl:15 row_mask:0xf bank_mask:0xf
	v_fmac_f32_dpp v109, v89, v229 row_shl:15 row_mask:0xf bank_mask:0xf
	v_fmac_f32_dpp v110, v82, v242 row_shl:15 row_mask:0xf bank_mask:0xf
	v_fmac_f32_dpp v111, v83, v243 row_shl:15 row_mask:0xf bank_mask:0xf
	v_fmac_f32_dpp v112, v84, v244 row_shl:15 row_mask:0xf bank_mask:0xf
	v_fmac_f32_dpp v113, v85, v245 row_shl:15 row_mask:0xf bank_mask:0xf
	v_fmac_f32_dpp v106, v86, v230 row_shl:14 row_mask:0xf bank_mask:0xf
	v_fmac_f32_dpp v107, v87, v231 row_shl:14 row_mask:0xf bank_mask:0xf
	v_fmac_f32_dpp v108, v88, v232 row_shl:14 row_mask:0xf bank_mask:0xf
	v_fmac_f32_dpp v109, v89, v233 row_shl:14 row_mask:0xf bank_mask:0xf
	v_fmac_f32_dpp v110, v82, v246 row_shl:14 row_mask:0xf bank_mask:0xf
	v_fmac_f32_dpp v111, v83, v247 row_shl:14 row_mask:0xf bank_mask:0xf
	v_fmac_f32_dpp v112, v84, v248 row_shl:14 row_mask:0xf bank_mask:0xf
	v_fmac_f32_dpp v113, v85, v249 row_shl:14 row_mask:0xf bank_mask:0xf
	v_pk_mul_f32 v[114:115], v[106:107], v[106:107]
	v_pk_mul_f32 v[116:117], v[108:109], v[108:109]
	v_pk_fma_f32 v[114:115], v[114:115], v[132:133], v[196:197] op_sel_hi:[1,0,0]
	v_pk_fma_f32 v[116:117], v[116:117], v[132:133], v[196:197] op_sel_hi:[1,0,0]
	v_pk_mul_f32 v[114:115], v[106:107], v[114:115]
	v_pk_mul_f32 v[116:117], v[108:109], v[116:117]
	v_exp_f32_e32 v114, v114
	v_exp_f32_e32 v115, v115
	v_exp_f32_e32 v116, v116
	v_exp_f32_e32 v117, v117
	v_pk_add_f32 v[114:115], v[114:115], v[250:251] op_sel_hi:[1,0]
	v_pk_add_f32 v[116:117], v[116:117], v[250:251] op_sel_hi:[1,0]
	v_rcp_f32_e32 v114, v114
	v_rcp_f32_e32 v115, v115
	v_rcp_f32_e32 v116, v116
	v_rcp_f32_e32 v117, v117
	v_pk_mul_f32 v[114:115], v[106:107], v[114:115]
	v_pk_mul_f32 v[116:117], v[108:109], v[116:117]
	v_pk_mul_f32 v[114:115], v[110:111], v[114:115]
	v_pk_mul_f32 v[116:117], v[112:113], v[116:117]
	v_cvt_pk_bf16_f32 v114, v114, v115
	v_cvt_pk_bf16_f32 v115, v116, v117
	v_add_u32_e32 v130, 0x1b8000, v199
	global_store_dwordx2 v130, v[114:115], s[68:69]
	v_pk_mul_f32 v[70:71], v[70:71], v[178:179] op_sel_hi:[1,0]
	v_pk_mul_f32 v[72:73], v[72:73], v[178:179] op_sel_hi:[1,0]
	v_pk_mul_f32 v[66:67], v[66:67], v[178:179] op_sel_hi:[1,0]
	v_pk_mul_f32 v[68:69], v[68:69], v[178:179] op_sel_hi:[1,0]
	v_pk_fma_f32 v[118:119], v[70:71], v[218:219], v[222:223]
	v_pk_fma_f32 v[120:121], v[72:73], v[220:221], v[224:225]
	v_pk_fma_f32 v[122:123], v[66:67], v[234:235], v[238:239]
	v_pk_fma_f32 v[124:125], v[68:69], v[236:237], v[240:241]
	v_fmac_f32_dpp v118, v70, v226 row_shr:1 row_mask:0xf bank_mask:0xf
	v_fmac_f32_dpp v119, v71, v227 row_shr:1 row_mask:0xf bank_mask:0xf
	v_fmac_f32_dpp v120, v72, v228 row_shr:1 row_mask:0xf bank_mask:0xf
	v_fmac_f32_dpp v121, v73, v229 row_shr:1 row_mask:0xf bank_mask:0xf
	v_fmac_f32_dpp v122, v66, v242 row_shr:1 row_mask:0xf bank_mask:0xf
	v_fmac_f32_dpp v123, v67, v243 row_shr:1 row_mask:0xf bank_mask:0xf
	v_fmac_f32_dpp v124, v68, v244 row_shr:1 row_mask:0xf bank_mask:0xf
	v_fmac_f32_dpp v125, v69, v245 row_shr:1 row_mask:0xf bank_mask:0xf
	v_fmac_f32_dpp v118, v70, v230 row_shr:2 row_mask:0xf bank_mask:0xf
	v_fmac_f32_dpp v119, v71, v231 row_shr:2 row_mask:0xf bank_mask:0xf
	v_fmac_f32_dpp v120, v72, v232 row_shr:2 row_mask:0xf bank_mask:0xf
	v_fmac_f32_dpp v121, v73, v233 row_shr:2 row_mask:0xf bank_mask:0xf
	v_fmac_f32_dpp v122, v66, v246 row_shr:2 row_mask:0xf bank_mask:0xf
	v_fmac_f32_dpp v123, v67, v247 row_shr:2 row_mask:0xf bank_mask:0xf
	v_fmac_f32_dpp v124, v68, v248 row_shr:2 row_mask:0xf bank_mask:0xf
	v_fmac_f32_dpp v125, v69, v249 row_shr:2 row_mask:0xf bank_mask:0xf
	v_fmac_f32_dpp v118, v78, v226 row_shl:15 row_mask:0xf bank_mask:0xf
	v_fmac_f32_dpp v119, v79, v227 row_shl:15 row_mask:0xf bank_mask:0xf
	v_fmac_f32_dpp v120, v80, v228 row_shl:15 row_mask:0xf bank_mask:0xf
	v_fmac_f32_dpp v121, v81, v229 row_shl:15 row_mask:0xf bank_mask:0xf
	v_fmac_f32_dpp v122, v74, v242 row_shl:15 row_mask:0xf bank_mask:0xf
	v_fmac_f32_dpp v123, v75, v243 row_shl:15 row_mask:0xf bank_mask:0xf
	v_fmac_f32_dpp v124, v76, v244 row_shl:15 row_mask:0xf bank_mask:0xf
	v_fmac_f32_dpp v125, v77, v245 row_shl:15 row_mask:0xf bank_mask:0xf
	v_fmac_f32_dpp v118, v78, v230 row_shl:14 row_mask:0xf bank_mask:0xf
; __device__ __forceinline__ unsigned cvt_pk_bf16(float lo, float hi) { unsigned r; asm volatile("v_cvt_pk_bf16_f32 %0, %1, %2" : "=v"(r) : "v"(lo), "v"(hi)); return r; }
; __device__ __forceinline__ f32x4 gelu4(f32x4 v) { return (f32x4){gelu_t(v[0]), gelu_t(v[1]), gelu_t(v[2]), gelu_t(v[3])}; }
; template <int CTRL> __device__ __forceinline__ f32x4 dpp4(f32x4 v) { return (f32x4){dpp_f<CTRL>(v[0]), dpp_f<CTRL>(v[1]), dpp_f<CTRL>(v[2]), dpp_f<CTRL>(v[3])}; }
;     __device__ __forceinline__ void operator()(const f32x4 (&acc)[2][2][4][2], const Unit& u, int wr, int wc, int fr, int fq) const {
;     ...
;                     for (int m = 0; m < 4; ++m) {
;                         const f32x4 g = acc[ai][0][m][n] * rs[ai][m], v = acc[ai][1][m][n] * rs[ai][m];
;                         const f32x4 g1 = dpp4<0x121>(g), g2 = dpp4<0x122>(g), v1 = dpp4<0x121>(v), v2 = dpp4<0x122>(v);
;                         const f32x4 gp1 = (fr >= 1) ? g1 : pg1, gp2 = (fr >= 2) ? g2 : pg2, vp1 = (fr >= 1) ? v1 : pv1, vp2 = (fr >= 2) ? v2 : pv2;
;                         const f32x4 cgt = bg + wg0 * g + wg1 * gp1 + wg2 * gp2, cvl = bv + wv0 * v + wv1 * vp1 + wv2 * vp2;
;                         const f32x4 o = gelu4(cgt) * cvl;
;                         typedef unsigned u32x2e __attribute__((ext_vector_type(2)));
;                         u32x2e w; w.x = cvt_pk_bf16(o[0], o[1]); w.y = cvt_pk_bf16(o[2], o[3]);
;                         if (!(m == 0 && fr < 2)) *(u32x2e*)((bf16_t*)O + (size_t)(row0 + ai * HALF + m * 16) * DFFc + c) = w;
	v_fmac_f32_dpp v119, v79, v231 row_shl:14 row_mask:0xf bank_mask:0xf
	v_fmac_f32_dpp v120, v80, v232 row_shl:14 row_mask:0xf bank_mask:0xf
	v_fmac_f32_dpp v121, v81, v233 row_shl:14 row_mask:0xf bank_mask:0xf
	v_fmac_f32_dpp v122, v74, v246 row_shl:14 row_mask:0xf bank_mask:0xf
	v_fmac_f32_dpp v123, v75, v247 row_shl:14 row_mask:0xf bank_mask:0xf
	v_fmac_f32_dpp v124, v76, v248 row_shl:14 row_mask:0xf bank_mask:0xf
	v_fmac_f32_dpp v125, v77, v249 row_shl:14 row_mask:0xf bank_mask:0xf
	v_pk_mul_f32 v[126:127], v[118:119], v[118:119]
	v_pk_mul_f32 v[128:129], v[120:121], v[120:121]
	v_pk_fma_f32 v[126:127], v[126:127], v[132:133], v[196:197] op_sel_hi:[1,0,0]
	v_pk_fma_f32 v[128:129], v[128:129], v[132:133], v[196:197] op_sel_hi:[1,0,0]
	v_pk_mul_f32 v[126:127], v[118:119], v[126:127]
	v_pk_mul_f32 v[128:129], v[120:121], v[128:129]
	v_exp_f32_e32 v126, v126
	v_exp_f32_e32 v127, v127
	v_exp_f32_e32 v128, v128
	v_exp_f32_e32 v129, v129
	v_pk_add_f32 v[126:127], v[126:127], v[250:251] op_sel_hi:[1,0]
	v_pk_add_f32 v[128:129], v[128:129], v[250:251] op_sel_hi:[1,0]
	v_rcp_f32_e32 v126, v126
	v_rcp_f32_e32 v127, v127
	v_rcp_f32_e32 v128, v128
	v_rcp_f32_e32 v129, v129
	v_pk_mul_f32 v[126:127], v[118:119], v[126:127]
	v_pk_mul_f32 v[128:129], v[120:121], v[128:129]
	v_pk_mul_f32 v[126:127], v[122:123], v[126:127]
	v_pk_mul_f32 v[128:129], v[124:125], v[128:129]
	v_cvt_pk_bf16_f32 v126, v126, v127
	v_cvt_pk_bf16_f32 v127, v128, v129
	v_add_u32_e32 v131, 0x1e4000, v199
	global_store_dwordx2 v131, v[126:127], s[68:69]
	s_waitcnt vmcnt(4)
	s_nop 0
	v_pk_mul_f32 v[62:63], v[62:63], v[188:189] op_sel_hi:[1,0]
	v_pk_mul_f32 v[64:65], v[64:65], v[188:189] op_sel_hi:[1,0]
	v_pk_mul_f32 v[58:59], v[58:59], v[188:189] op_sel_hi:[1,0]
	v_pk_mul_f32 v[60:61], v[60:61], v[188:189] op_sel_hi:[1,0]
	v_pk_fma_f32 v[106:107], v[62:63], v[154:155], v[150:151]
	v_pk_fma_f32 v[108:109], v[64:65], v[156:157], v[152:153]
	v_pk_fma_f32 v[110:111], v[58:59], v[134:135], v[146:147]
	v_pk_fma_f32 v[112:113], v[60:61], v[136:137], v[148:149]
	v_fmac_f32_dpp v106, v62, v142 row_shr:1 row_mask:0xf bank_mask:0xf
	v_fmac_f32_dpp v107, v63, v143 row_shr:1 row_mask:0xf bank_mask:0xf
	v_fmac_f32_dpp v108, v64, v144 row_shr:1 row_mask:0xf bank_mask:0xf
	v_fmac_f32_dpp v109, v65, v145 row_shr:1 row_mask:0xf bank_mask:0xf
	v_fmac_f32_dpp v110, v58, v138 row_shr:1 row_mask:0xf bank_mask:0xf
	v_fmac_f32_dpp v111, v59, v139 row_shr:1 row_mask:0xf bank_mask:0xf
	v_fmac_f32_dpp v112, v60, v140 row_shr:1 row_mask:0xf bank_mask:0xf
	v_fmac_f32_dpp v113, v61, v141 row_shr:1 row_mask:0xf bank_mask:0xf
	v_fmac_f32_dpp v106, v62, v102 row_shr:2 row_mask:0xf bank_mask:0xf
	v_fmac_f32_dpp v107, v63, v103 row_shr:2 row_mask:0xf bank_mask:0xf
	v_fmac_f32_dpp v108, v64, v104 row_shr:2 row_mask:0xf bank_mask:0xf
	v_fmac_f32_dpp v109, v65, v105 row_shr:2 row_mask:0xf bank_mask:0xf
	v_fmac_f32_dpp v110, v58, v98 row_shr:2 row_mask:0xf bank_mask:0xf
	v_fmac_f32_dpp v111, v59, v99 row_shr:2 row_mask:0xf bank_mask:0xf
	v_fmac_f32_dpp v112, v60, v100 row_shr:2 row_mask:0xf bank_mask:0xf
	v_fmac_f32_dpp v113, v61, v101 row_shr:2 row_mask:0xf bank_mask:0xf
	v_pk_mul_f32 v[114:115], v[106:107], v[106:107]
	v_pk_mul_f32 v[116:117], v[108:109], v[108:109]
	v_pk_fma_f32 v[114:115], v[114:115], v[132:133], v[196:197] op_sel_hi:[1,0,0]
	v_pk_fma_f32 v[116:117], v[116:117], v[132:133], v[196:197] op_sel_hi:[1,0,0]
	v_pk_mul_f32 v[114:115], v[106:107], v[114:115]
	v_pk_mul_f32 v[116:117], v[108:109], v[116:117]
	v_exp_f32_e32 v114, v114
	v_exp_f32_e32 v115, v115
	v_exp_f32_e32 v116, v116
	v_exp_f32_e32 v117, v117
	v_pk_add_f32 v[114:115], v[114:115], v[250:251] op_sel_hi:[1,0]
	v_pk_add_f32 v[116:117], v[116:117], v[250:251] op_sel_hi:[1,0]
	v_rcp_f32_e32 v114, v114
	v_rcp_f32_e32 v115, v115
	v_rcp_f32_e32 v116, v116
	v_rcp_f32_e32 v117, v117
	v_pk_mul_f32 v[114:115], v[106:107], v[114:115]
	v_pk_mul_f32 v[116:117], v[108:109], v[116:117]
	v_pk_mul_f32 v[114:115], v[110:111], v[114:115]
	v_pk_mul_f32 v[116:117], v[112:113], v[116:117]
	v_cvt_pk_bf16_f32 v114, v114, v115
	v_cvt_pk_bf16_f32 v115, v116, v117
	s_and_saveexec_b64 s[48:49], s[10:11]
	global_store_dwordx2 v199, v[114:115], s[68:69] offset:8
	s_or_b64 exec, exec, s[48:49]
	v_pk_mul_f32 v[54:55], v[54:55], v[190:191] op_sel_hi:[1,0]
	v_pk_mul_f32 v[56:57], v[56:57], v[190:191] op_sel_hi:[1,0]
	v_pk_mul_f32 v[50:51], v[50:51], v[190:191] op_sel_hi:[1,0]
	v_pk_mul_f32 v[52:53], v[52:53], v[190:191] op_sel_hi:[1,0]
	v_pk_fma_f32 v[118:119], v[54:55], v[154:155], v[150:151]
	v_pk_fma_f32 v[120:121], v[56:57], v[156:157], v[152:153]
	v_pk_fma_f32 v[122:123], v[50:51], v[134:135], v[146:147]
	v_pk_fma_f32 v[124:125], v[52:53], v[136:137], v[148:149]
	v_fmac_f32_dpp v118, v54, v142 row_shr:1 row_mask:0xf bank_mask:0xf
	v_fmac_f32_dpp v119, v55, v143 row_shr:1 row_mask:0xf bank_mask:0xf
	v_fmac_f32_dpp v120, v56, v144 row_shr:1 row_mask:0xf bank_mask:0xf
	v_fmac_f32_dpp v121, v57, v145 row_shr:1 row_mask:0xf bank_mask:0xf
	v_fmac_f32_dpp v122, v50, v138 row_shr:1 row_mask:0xf bank_mask:0xf
	v_fmac_f32_dpp v123, v51, v139 row_shr:1 row_mask:0xf bank_mask:0xf
	v_fmac_f32_dpp v124, v52, v140 row_shr:1 row_mask:0xf bank_mask:0xf
	v_fmac_f32_dpp v125, v53, v141 row_shr:1 row_mask:0xf bank_mask:0xf
	v_fmac_f32_dpp v118, v54, v102 row_shr:2 row_mask:0xf bank_mask:0xf
	v_fmac_f32_dpp v119, v55, v103 row_shr:2 row_mask:0xf bank_mask:0xf
	v_fmac_f32_dpp v120, v56, v104 row_shr:2 row_mask:0xf bank_mask:0xf
	v_fmac_f32_dpp v121, v57, v105 row_shr:2 row_mask:0xf bank_mask:0xf
	v_fmac_f32_dpp v122, v50, v98 row_shr:2 row_mask:0xf bank_mask:0xf
; __device__ __forceinline__ unsigned cvt_pk_bf16(float lo, float hi) { unsigned r; asm volatile("v_cvt_pk_bf16_f32 %0, %1, %2" : "=v"(r) : "v"(lo), "v"(hi)); return r; }
; __device__ __forceinline__ f32x4 gelu4(f32x4 v) { return (f32x4){gelu_t(v[0]), gelu_t(v[1]), gelu_t(v[2]), gelu_t(v[3])}; }
; template <int CTRL> __device__ __forceinline__ f32x4 dpp4(f32x4 v) { return (f32x4){dpp_f<CTRL>(v[0]), dpp_f<CTRL>(v[1]), dpp_f<CTRL>(v[2]), dpp_f<CTRL>(v[3])}; }
;     __device__ __forceinline__ void operator()(const f32x4 (&acc)[2][2][4][2], const Unit& u, int wr, int wc, int fr, int fq) const {
;     ...
;                     for (int m = 0; m < 4; ++m) {
;                         const f32x4 g = acc[ai][0][m][n] * rs[ai][m], v = acc[ai][1][m][n] * rs[ai][m];
;                         const f32x4 g1 = dpp4<0x121>(g), g2 = dpp4<0x122>(g), v1 = dpp4<0x121>(v), v2 = dpp4<0x122>(v);
;                         const f32x4 gp1 = (fr >= 1) ? g1 : pg1, gp2 = (fr >= 2) ? g2 : pg2, vp1 = (fr >= 1) ? v1 : pv1, vp2 = (fr >= 2) ? v2 : pv2;
;                         const f32x4 cgt = bg + wg0 * g + wg1 * gp1 + wg2 * gp2, cvl = bv + wv0 * v + wv1 * vp1 + wv2 * vp2;
;                         const f32x4 o = gelu4(cgt) * cvl;
;                         typedef unsigned u32x2e __attribute__((ext_vector_type(2)));
;                         u32x2e w; w.x = cvt_pk_bf16(o[0], o[1]); w.y = cvt_pk_bf16(o[2], o[3]);
;                         if (!(m == 0 && fr < 2)) *(u32x2e*)((bf16_t*)O + (size_t)(row0 + ai * HALF + m * 16) * DFFc + c) = w;
	v_fmac_f32_dpp v123, v51, v99 row_shr:2 row_mask:0xf bank_mask:0xf
	v_fmac_f32_dpp v124, v52, v100 row_shr:2 row_mask:0xf bank_mask:0xf
	v_fmac_f32_dpp v125, v53, v101 row_shr:2 row_mask:0xf bank_mask:0xf
	v_fmac_f32_dpp v118, v62, v142 row_shl:15 row_mask:0xf bank_mask:0xf
	v_fmac_f32_dpp v119, v63, v143 row_shl:15 row_mask:0xf bank_mask:0xf
	v_fmac_f32_dpp v120, v64, v144 row_shl:15 row_mask:0xf bank_mask:0xf
	v_fmac_f32_dpp v121, v65, v145 row_shl:15 row_mask:0xf bank_mask:0xf
	v_fmac_f32_dpp v122, v58, v138 row_shl:15 row_mask:0xf bank_mask:0xf
	v_fmac_f32_dpp v123, v59, v139 row_shl:15 row_mask:0xf bank_mask:0xf
	v_fmac_f32_dpp v124, v60, v140 row_shl:15 row_mask:0xf bank_mask:0xf
	v_fmac_f32_dpp v125, v61, v141 row_shl:15 row_mask:0xf bank_mask:0xf
	v_fmac_f32_dpp v118, v62, v102 row_shl:14 row_mask:0xf bank_mask:0xf
	v_fmac_f32_dpp v119, v63, v103 row_shl:14 row_mask:0xf bank_mask:0xf
	v_fmac_f32_dpp v120, v64, v104 row_shl:14 row_mask:0xf bank_mask:0xf
	v_fmac_f32_dpp v121, v65, v105 row_shl:14 row_mask:0xf bank_mask:0xf
	v_fmac_f32_dpp v122, v58, v98 row_shl:14 row_mask:0xf bank_mask:0xf
	v_fmac_f32_dpp v123, v59, v99 row_shl:14 row_mask:0xf bank_mask:0xf
	v_fmac_f32_dpp v124, v60, v100 row_shl:14 row_mask:0xf bank_mask:0xf
	v_fmac_f32_dpp v125, v61, v101 row_shl:14 row_mask:0xf bank_mask:0xf
	v_pk_mul_f32 v[126:127], v[118:119], v[118:119]
	v_pk_mul_f32 v[128:129], v[120:121], v[120:121]
	v_pk_fma_f32 v[126:127], v[126:127], v[132:133], v[196:197] op_sel_hi:[1,0,0]
	v_pk_fma_f32 v[128:129], v[128:129], v[132:133], v[196:197] op_sel_hi:[1,0,0]
	v_pk_mul_f32 v[126:127], v[118:119], v[126:127]
	v_pk_mul_f32 v[128:129], v[120:121], v[128:129]
	v_exp_f32_e32 v126, v126
	v_exp_f32_e32 v127, v127
	v_exp_f32_e32 v128, v128
	v_exp_f32_e32 v129, v129
	v_pk_add_f32 v[126:127], v[126:127], v[250:251] op_sel_hi:[1,0]
	v_pk_add_f32 v[128:129], v[128:129], v[250:251] op_sel_hi:[1,0]
	v_rcp_f32_e32 v126, v126
	v_rcp_f32_e32 v127, v127
	v_rcp_f32_e32 v128, v128
	v_rcp_f32_e32 v129, v129
	v_pk_mul_f32 v[126:127], v[118:119], v[126:127]
	v_pk_mul_f32 v[128:129], v[120:121], v[128:129]
	v_pk_mul_f32 v[126:127], v[122:123], v[126:127]
	v_pk_mul_f32 v[128:129], v[124:125], v[128:129]
	v_cvt_pk_bf16_f32 v126, v126, v127
	v_cvt_pk_bf16_f32 v127, v128, v129
	v_add_u32_e32 v131, 0x2c000, v199
	global_store_dwordx2 v131, v[126:127], s[68:69] offset:8
	v_pk_mul_f32 v[46:47], v[46:47], v[192:193] op_sel_hi:[1,0]
	v_pk_mul_f32 v[48:49], v[48:49], v[192:193] op_sel_hi:[1,0]
	v_pk_mul_f32 v[42:43], v[42:43], v[192:193] op_sel_hi:[1,0]
	v_pk_mul_f32 v[44:45], v[44:45], v[192:193] op_sel_hi:[1,0]
	v_pk_fma_f32 v[106:107], v[46:47], v[154:155], v[150:151]
	v_pk_fma_f32 v[108:109], v[48:49], v[156:157], v[152:153]
	v_pk_fma_f32 v[110:111], v[42:43], v[134:135], v[146:147]
	v_pk_fma_f32 v[112:113], v[44:45], v[136:137], v[148:149]
	v_fmac_f32_dpp v106, v46, v142 row_shr:1 row_mask:0xf bank_mask:0xf
	v_fmac_f32_dpp v107, v47, v143 row_shr:1 row_mask:0xf bank_mask:0xf
	v_fmac_f32_dpp v108, v48, v144 row_shr:1 row_mask:0xf bank_mask:0xf
	v_fmac_f32_dpp v109, v49, v145 row_shr:1 row_mask:0xf bank_mask:0xf
	v_fmac_f32_dpp v110, v42, v138 row_shr:1 row_mask:0xf bank_mask:0xf
	v_fmac_f32_dpp v111, v43, v139 row_shr:1 row_mask:0xf bank_mask:0xf
	v_fmac_f32_dpp v112, v44, v140 row_shr:1 row_mask:0xf bank_mask:0xf
	v_fmac_f32_dpp v113, v45, v141 row_shr:1 row_mask:0xf bank_mask:0xf
	v_fmac_f32_dpp v106, v46, v102 row_shr:2 row_mask:0xf bank_mask:0xf
	v_fmac_f32_dpp v107, v47, v103 row_shr:2 row_mask:0xf bank_mask:0xf
	v_fmac_f32_dpp v108, v48, v104 row_shr:2 row_mask:0xf bank_mask:0xf
	v_fmac_f32_dpp v109, v49, v105 row_shr:2 row_mask:0xf bank_mask:0xf
	v_fmac_f32_dpp v110, v42, v98 row_shr:2 row_mask:0xf bank_mask:0xf
	v_fmac_f32_dpp v111, v43, v99 row_shr:2 row_mask:0xf bank_mask:0xf
	v_fmac_f32_dpp v112, v44, v100 row_shr:2 row_mask:0xf bank_mask:0xf
	v_fmac_f32_dpp v113, v45, v101 row_shr:2 row_mask:0xf bank_mask:0xf
	v_fmac_f32_dpp v106, v54, v142 row_shl:15 row_mask:0xf bank_mask:0xf
	v_fmac_f32_dpp v107, v55, v143 row_shl:15 row_mask:0xf bank_mask:0xf
	v_fmac_f32_dpp v108, v56, v144 row_shl:15 row_mask:0xf bank_mask:0xf
	v_fmac_f32_dpp v109, v57, v145 row_shl:15 row_mask:0xf bank_mask:0xf
	v_fmac_f32_dpp v110, v50, v138 row_shl:15 row_mask:0xf bank_mask:0xf
	v_fmac_f32_dpp v111, v51, v139 row_shl:15 row_mask:0xf bank_mask:0xf
	v_fmac_f32_dpp v112, v52, v140 row_shl:15 row_mask:0xf bank_mask:0xf
	v_fmac_f32_dpp v113, v53, v141 row_shl:15 row_mask:0xf bank_mask:0xf
	v_fmac_f32_dpp v106, v54, v102 row_shl:14 row_mask:0xf bank_mask:0xf
	v_fmac_f32_dpp v107, v55, v103 row_shl:14 row_mask:0xf bank_mask:0xf
	v_fmac_f32_dpp v108, v56, v104 row_shl:14 row_mask:0xf bank_mask:0xf
	v_fmac_f32_dpp v109, v57, v105 row_shl:14 row_mask:0xf bank_mask:0xf
	v_fmac_f32_dpp v110, v50, v98 row_shl:14 row_mask:0xf bank_mask:0xf
	v_fmac_f32_dpp v111, v51, v99 row_shl:14 row_mask:0xf bank_mask:0xf
	v_fmac_f32_dpp v112, v52, v100 row_shl:14 row_mask:0xf bank_mask:0xf
	v_fmac_f32_dpp v113, v53, v101 row_shl:14 row_mask:0xf bank_mask:0xf
	v_pk_mul_f32 v[114:115], v[106:107], v[106:107]
	v_pk_mul_f32 v[116:117], v[108:109], v[108:109]
	v_pk_fma_f32 v[114:115], v[114:115], v[132:133], v[196:197] op_sel_hi:[1,0,0]
	v_pk_fma_f32 v[116:117], v[116:117], v[132:133], v[196:197] op_sel_hi:[1,0,0]
	v_pk_mul_f32 v[114:115], v[106:107], v[114:115]
	v_pk_mul_f32 v[116:117], v[108:109], v[116:117]
	v_exp_f32_e32 v114, v114
	v_exp_f32_e32 v115, v115
	v_exp_f32_e32 v116, v116
	v_exp_f32_e32 v117, v117
	v_pk_add_f32 v[114:115], v[114:115], v[250:251] op_sel_hi:[1,0]
	v_pk_add_f32 v[116:117], v[116:117], v[250:251] op_sel_hi:[1,0]
; __device__ __forceinline__ unsigned cvt_pk_bf16(float lo, float hi) { unsigned r; asm volatile("v_cvt_pk_bf16_f32 %0, %1, %2" : "=v"(r) : "v"(lo), "v"(hi)); return r; }
; __device__ __forceinline__ f32x4 gelu4(f32x4 v) { return (f32x4){gelu_t(v[0]), gelu_t(v[1]), gelu_t(v[2]), gelu_t(v[3])}; }
; template <int CTRL> __device__ __forceinline__ f32x4 dpp4(f32x4 v) { return (f32x4){dpp_f<CTRL>(v[0]), dpp_f<CTRL>(v[1]), dpp_f<CTRL>(v[2]), dpp_f<CTRL>(v[3])}; }
;     __device__ __forceinline__ void operator()(const f32x4 (&acc)[2][2][4][2], const Unit& u, int wr, int wc, int fr, int fq) const {
;     ...
;                     for (int m = 0; m < 4; ++m) {
;                         const f32x4 g = acc[ai][0][m][n] * rs[ai][m], v = acc[ai][1][m][n] * rs[ai][m];
;                         const f32x4 g1 = dpp4<0x121>(g), g2 = dpp4<0x122>(g), v1 = dpp4<0x121>(v), v2 = dpp4<0x122>(v);
;                         const f32x4 gp1 = (fr >= 1) ? g1 : pg1, gp2 = (fr >= 2) ? g2 : pg2, vp1 = (fr >= 1) ? v1 : pv1, vp2 = (fr >= 2) ? v2 : pv2;
;                         const f32x4 cgt = bg + wg0 * g + wg1 * gp1 + wg2 * gp2, cvl = bv + wv0 * v + wv1 * vp1 + wv2 * vp2;
;                         const f32x4 o = gelu4(cgt) * cvl;
;                         typedef unsigned u32x2e __attribute__((ext_vector_type(2)));
;                         u32x2e w; w.x = cvt_pk_bf16(o[0], o[1]); w.y = cvt_pk_bf16(o[2], o[3]);
;                         if (!(m == 0 && fr < 2)) *(u32x2e*)((bf16_t*)O + (size_t)(row0 + ai * HALF + m * 16) * DFFc + c) = w;
	v_rcp_f32_e32 v114, v114
	v_rcp_f32_e32 v115, v115
	v_rcp_f32_e32 v116, v116
	v_rcp_f32_e32 v117, v117
	v_pk_mul_f32 v[114:115], v[106:107], v[114:115]
	v_pk_mul_f32 v[116:117], v[108:109], v[116:117]
	v_pk_mul_f32 v[114:115], v[110:111], v[114:115]
	v_pk_mul_f32 v[116:117], v[112:113], v[116:117]
	v_cvt_pk_bf16_f32 v114, v114, v115
	v_cvt_pk_bf16_f32 v115, v116, v117
	v_add_u32_e32 v130, 0x58000, v199
	global_store_dwordx2 v130, v[114:115], s[68:69] offset:8
	v_pk_mul_f32 v[38:39], v[38:39], v[184:185] op_sel_hi:[1,0]
	v_pk_mul_f32 v[40:41], v[40:41], v[184:185] op_sel_hi:[1,0]
	v_pk_mul_f32 v[34:35], v[34:35], v[184:185] op_sel_hi:[1,0]
	v_pk_mul_f32 v[36:37], v[36:37], v[184:185] op_sel_hi:[1,0]
	v_pk_fma_f32 v[118:119], v[38:39], v[154:155], v[150:151]
	v_pk_fma_f32 v[120:121], v[40:41], v[156:157], v[152:153]
	v_pk_fma_f32 v[122:123], v[34:35], v[134:135], v[146:147]
	v_pk_fma_f32 v[124:125], v[36:37], v[136:137], v[148:149]
	v_fmac_f32_dpp v118, v38, v142 row_shr:1 row_mask:0xf bank_mask:0xf
	v_fmac_f32_dpp v119, v39, v143 row_shr:1 row_mask:0xf bank_mask:0xf
	v_fmac_f32_dpp v120, v40, v144 row_shr:1 row_mask:0xf bank_mask:0xf
	v_fmac_f32_dpp v121, v41, v145 row_shr:1 row_mask:0xf bank_mask:0xf
	v_fmac_f32_dpp v122, v34, v138 row_shr:1 row_mask:0xf bank_mask:0xf
	v_fmac_f32_dpp v123, v35, v139 row_shr:1 row_mask:0xf bank_mask:0xf
	v_fmac_f32_dpp v124, v36, v140 row_shr:1 row_mask:0xf bank_mask:0xf
	v_fmac_f32_dpp v125, v37, v141 row_shr:1 row_mask:0xf bank_mask:0xf
	v_fmac_f32_dpp v118, v38, v102 row_shr:2 row_mask:0xf bank_mask:0xf
	v_fmac_f32_dpp v119, v39, v103 row_shr:2 row_mask:0xf bank_mask:0xf
	v_fmac_f32_dpp v120, v40, v104 row_shr:2 row_mask:0xf bank_mask:0xf
	v_fmac_f32_dpp v121, v41, v105 row_shr:2 row_mask:0xf bank_mask:0xf
	v_fmac_f32_dpp v122, v34, v98 row_shr:2 row_mask:0xf bank_mask:0xf
	v_fmac_f32_dpp v123, v35, v99 row_shr:2 row_mask:0xf bank_mask:0xf
	v_fmac_f32_dpp v124, v36, v100 row_shr:2 row_mask:0xf bank_mask:0xf
	v_fmac_f32_dpp v125, v37, v101 row_shr:2 row_mask:0xf bank_mask:0xf
	v_fmac_f32_dpp v118, v46, v142 row_shl:15 row_mask:0xf bank_mask:0xf
	v_fmac_f32_dpp v119, v47, v143 row_shl:15 row_mask:0xf bank_mask:0xf
	v_fmac_f32_dpp v120, v48, v144 row_shl:15 row_mask:0xf bank_mask:0xf
	v_fmac_f32_dpp v121, v49, v145 row_shl:15 row_mask:0xf bank_mask:0xf
	v_fmac_f32_dpp v122, v42, v138 row_shl:15 row_mask:0xf bank_mask:0xf
	v_fmac_f32_dpp v123, v43, v139 row_shl:15 row_mask:0xf bank_mask:0xf
	v_fmac_f32_dpp v124, v44, v140 row_shl:15 row_mask:0xf bank_mask:0xf
	v_fmac_f32_dpp v125, v45, v141 row_shl:15 row_mask:0xf bank_mask:0xf
	v_fmac_f32_dpp v118, v46, v102 row_shl:14 row_mask:0xf bank_mask:0xf
	v_fmac_f32_dpp v119, v47, v103 row_shl:14 row_mask:0xf bank_mask:0xf
	v_fmac_f32_dpp v120, v48, v104 row_shl:14 row_mask:0xf bank_mask:0xf
	v_fmac_f32_dpp v121, v49, v105 row_shl:14 row_mask:0xf bank_mask:0xf
	v_fmac_f32_dpp v122, v42, v98 row_shl:14 row_mask:0xf bank_mask:0xf
	v_fmac_f32_dpp v123, v43, v99 row_shl:14 row_mask:0xf bank_mask:0xf
	v_fmac_f32_dpp v124, v44, v100 row_shl:14 row_mask:0xf bank_mask:0xf
	v_fmac_f32_dpp v125, v45, v101 row_shl:14 row_mask:0xf bank_mask:0xf
	v_pk_mul_f32 v[126:127], v[118:119], v[118:119]
	v_pk_mul_f32 v[128:129], v[120:121], v[120:121]
	v_pk_fma_f32 v[126:127], v[126:127], v[132:133], v[196:197] op_sel_hi:[1,0,0]
	v_pk_fma_f32 v[128:129], v[128:129], v[132:133], v[196:197] op_sel_hi:[1,0,0]
	v_pk_mul_f32 v[126:127], v[118:119], v[126:127]
	v_pk_mul_f32 v[128:129], v[120:121], v[128:129]
	v_exp_f32_e32 v126, v126
	v_exp_f32_e32 v127, v127
	v_exp_f32_e32 v128, v128
	v_exp_f32_e32 v129, v129
	v_pk_add_f32 v[126:127], v[126:127], v[250:251] op_sel_hi:[1,0]
	v_pk_add_f32 v[128:129], v[128:129], v[250:251] op_sel_hi:[1,0]
	v_rcp_f32_e32 v126, v126
	v_rcp_f32_e32 v127, v127
	v_rcp_f32_e32 v128, v128
	v_rcp_f32_e32 v129, v129
	v_pk_mul_f32 v[126:127], v[118:119], v[126:127]
	v_pk_mul_f32 v[128:129], v[120:121], v[128:129]
	v_pk_mul_f32 v[126:127], v[122:123], v[126:127]
	v_pk_mul_f32 v[128:129], v[124:125], v[128:129]
	v_cvt_pk_bf16_f32 v126, v126, v127
	v_cvt_pk_bf16_f32 v127, v128, v129
	v_add_u32_e32 v131, 0x84000, v199
	global_store_dwordx2 v131, v[126:127], s[68:69] offset:8
	v_pk_mul_f32 v[30:31], v[30:31], v[182:183] op_sel_hi:[1,0]
	v_pk_mul_f32 v[32:33], v[32:33], v[182:183] op_sel_hi:[1,0]
	v_pk_mul_f32 v[26:27], v[26:27], v[182:183] op_sel_hi:[1,0]
	v_pk_mul_f32 v[28:29], v[28:29], v[182:183] op_sel_hi:[1,0]
	v_pk_fma_f32 v[106:107], v[30:31], v[154:155], v[150:151]
	v_pk_fma_f32 v[108:109], v[32:33], v[156:157], v[152:153]
	v_pk_fma_f32 v[110:111], v[26:27], v[134:135], v[146:147]
	v_pk_fma_f32 v[112:113], v[28:29], v[136:137], v[148:149]
	v_fmac_f32_dpp v106, v30, v142 row_shr:1 row_mask:0xf bank_mask:0xf
	v_fmac_f32_dpp v107, v31, v143 row_shr:1 row_mask:0xf bank_mask:0xf
	v_fmac_f32_dpp v108, v32, v144 row_shr:1 row_mask:0xf bank_mask:0xf
	v_fmac_f32_dpp v109, v33, v145 row_shr:1 row_mask:0xf bank_mask:0xf
	v_fmac_f32_dpp v110, v26, v138 row_shr:1 row_mask:0xf bank_mask:0xf
	v_fmac_f32_dpp v111, v27, v139 row_shr:1 row_mask:0xf bank_mask:0xf
	v_fmac_f32_dpp v112, v28, v140 row_shr:1 row_mask:0xf bank_mask:0xf
	v_fmac_f32_dpp v113, v29, v141 row_shr:1 row_mask:0xf bank_mask:0xf
	v_fmac_f32_dpp v106, v30, v102 row_shr:2 row_mask:0xf bank_mask:0xf
	v_fmac_f32_dpp v107, v31, v103 row_shr:2 row_mask:0xf bank_mask:0xf
	v_fmac_f32_dpp v108, v32, v104 row_shr:2 row_mask:0xf bank_mask:0xf
	v_fmac_f32_dpp v109, v33, v105 row_shr:2 row_mask:0xf bank_mask:0xf
	v_fmac_f32_dpp v110, v26, v98 row_shr:2 row_mask:0xf bank_mask:0xf
	v_fmac_f32_dpp v111, v27, v99 row_shr:2 row_mask:0xf bank_mask:0xf
; __device__ __forceinline__ unsigned cvt_pk_bf16(float lo, float hi) { unsigned r; asm volatile("v_cvt_pk_bf16_f32 %0, %1, %2" : "=v"(r) : "v"(lo), "v"(hi)); return r; }
; __device__ __forceinline__ f32x4 gelu4(f32x4 v) { return (f32x4){gelu_t(v[0]), gelu_t(v[1]), gelu_t(v[2]), gelu_t(v[3])}; }
; template <int CTRL> __device__ __forceinline__ f32x4 dpp4(f32x4 v) { return (f32x4){dpp_f<CTRL>(v[0]), dpp_f<CTRL>(v[1]), dpp_f<CTRL>(v[2]), dpp_f<CTRL>(v[3])}; }
;     __device__ __forceinline__ void operator()(const f32x4 (&acc)[2][2][4][2], const Unit& u, int wr, int wc, int fr, int fq) const {
;     ...
;                     for (int m = 0; m < 4; ++m) {
;                         const f32x4 g = acc[ai][0][m][n] * rs[ai][m], v = acc[ai][1][m][n] * rs[ai][m];
;                         const f32x4 g1 = dpp4<0x121>(g), g2 = dpp4<0x122>(g), v1 = dpp4<0x121>(v), v2 = dpp4<0x122>(v);
;                         const f32x4 gp1 = (fr >= 1) ? g1 : pg1, gp2 = (fr >= 2) ? g2 : pg2, vp1 = (fr >= 1) ? v1 : pv1, vp2 = (fr >= 2) ? v2 : pv2;
;                         const f32x4 cgt = bg + wg0 * g + wg1 * gp1 + wg2 * gp2, cvl = bv + wv0 * v + wv1 * vp1 + wv2 * vp2;
;                         const f32x4 o = gelu4(cgt) * cvl;
;                         typedef unsigned u32x2e __attribute__((ext_vector_type(2)));
;                         u32x2e w; w.x = cvt_pk_bf16(o[0], o[1]); w.y = cvt_pk_bf16(o[2], o[3]);
;                         if (!(m == 0 && fr < 2)) *(u32x2e*)((bf16_t*)O + (size_t)(row0 + ai * HALF + m * 16) * DFFc + c) = w;
	v_fmac_f32_dpp v112, v28, v100 row_shr:2 row_mask:0xf bank_mask:0xf
	v_fmac_f32_dpp v113, v29, v101 row_shr:2 row_mask:0xf bank_mask:0xf
	v_pk_mul_f32 v[114:115], v[106:107], v[106:107]
	v_pk_mul_f32 v[116:117], v[108:109], v[108:109]
	v_pk_fma_f32 v[114:115], v[114:115], v[132:133], v[196:197] op_sel_hi:[1,0,0]
	v_pk_fma_f32 v[116:117], v[116:117], v[132:133], v[196:197] op_sel_hi:[1,0,0]
	v_pk_mul_f32 v[114:115], v[106:107], v[114:115]
	v_pk_mul_f32 v[116:117], v[108:109], v[116:117]
	v_exp_f32_e32 v114, v114
	v_exp_f32_e32 v115, v115
	v_exp_f32_e32 v116, v116
	v_exp_f32_e32 v117, v117
	v_pk_add_f32 v[114:115], v[114:115], v[250:251] op_sel_hi:[1,0]
	v_pk_add_f32 v[116:117], v[116:117], v[250:251] op_sel_hi:[1,0]
	v_rcp_f32_e32 v114, v114
	v_rcp_f32_e32 v115, v115
	v_rcp_f32_e32 v116, v116
	v_rcp_f32_e32 v117, v117
	v_pk_mul_f32 v[114:115], v[106:107], v[114:115]
	v_pk_mul_f32 v[116:117], v[108:109], v[116:117]
	v_pk_mul_f32 v[114:115], v[110:111], v[114:115]
	v_pk_mul_f32 v[116:117], v[112:113], v[116:117]
	v_cvt_pk_bf16_f32 v114, v114, v115
	v_cvt_pk_bf16_f32 v115, v116, v117
	v_add_u32_e32 v130, 0x160000, v199
	s_and_saveexec_b64 s[48:49], s[10:11]
	global_store_dwordx2 v130, v[114:115], s[68:69] offset:8
	s_or_b64 exec, exec, s[48:49]
	v_pk_mul_f32 v[22:23], v[22:23], v[180:181] op_sel_hi:[1,0]
	v_pk_mul_f32 v[24:25], v[24:25], v[180:181] op_sel_hi:[1,0]
	v_pk_mul_f32 v[18:19], v[18:19], v[180:181] op_sel_hi:[1,0]
	v_pk_mul_f32 v[20:21], v[20:21], v[180:181] op_sel_hi:[1,0]
	v_pk_fma_f32 v[118:119], v[22:23], v[154:155], v[150:151]
	v_pk_fma_f32 v[120:121], v[24:25], v[156:157], v[152:153]
	v_pk_fma_f32 v[122:123], v[18:19], v[134:135], v[146:147]
	v_pk_fma_f32 v[124:125], v[20:21], v[136:137], v[148:149]
	v_fmac_f32_dpp v118, v22, v142 row_shr:1 row_mask:0xf bank_mask:0xf
	v_fmac_f32_dpp v119, v23, v143 row_shr:1 row_mask:0xf bank_mask:0xf
	v_fmac_f32_dpp v120, v24, v144 row_shr:1 row_mask:0xf bank_mask:0xf
	v_fmac_f32_dpp v121, v25, v145 row_shr:1 row_mask:0xf bank_mask:0xf
	v_fmac_f32_dpp v122, v18, v138 row_shr:1 row_mask:0xf bank_mask:0xf
	v_fmac_f32_dpp v123, v19, v139 row_shr:1 row_mask:0xf bank_mask:0xf
	v_fmac_f32_dpp v124, v20, v140 row_shr:1 row_mask:0xf bank_mask:0xf
	v_fmac_f32_dpp v125, v21, v141 row_shr:1 row_mask:0xf bank_mask:0xf
	v_fmac_f32_dpp v118, v22, v102 row_shr:2 row_mask:0xf bank_mask:0xf
	v_fmac_f32_dpp v119, v23, v103 row_shr:2 row_mask:0xf bank_mask:0xf
	v_fmac_f32_dpp v120, v24, v104 row_shr:2 row_mask:0xf bank_mask:0xf
	v_fmac_f32_dpp v121, v25, v105 row_shr:2 row_mask:0xf bank_mask:0xf
	v_fmac_f32_dpp v122, v18, v98 row_shr:2 row_mask:0xf bank_mask:0xf
	v_fmac_f32_dpp v123, v19, v99 row_shr:2 row_mask:0xf bank_mask:0xf
	v_fmac_f32_dpp v124, v20, v100 row_shr:2 row_mask:0xf bank_mask:0xf
	v_fmac_f32_dpp v125, v21, v101 row_shr:2 row_mask:0xf bank_mask:0xf
	v_fmac_f32_dpp v118, v30, v142 row_shl:15 row_mask:0xf bank_mask:0xf
	v_fmac_f32_dpp v119, v31, v143 row_shl:15 row_mask:0xf bank_mask:0xf
	v_fmac_f32_dpp v120, v32, v144 row_shl:15 row_mask:0xf bank_mask:0xf
	v_fmac_f32_dpp v121, v33, v145 row_shl:15 row_mask:0xf bank_mask:0xf
	v_fmac_f32_dpp v122, v26, v138 row_shl:15 row_mask:0xf bank_mask:0xf
	v_fmac_f32_dpp v123, v27, v139 row_shl:15 row_mask:0xf bank_mask:0xf
	v_fmac_f32_dpp v124, v28, v140 row_shl:15 row_mask:0xf bank_mask:0xf
	v_fmac_f32_dpp v125, v29, v141 row_shl:15 row_mask:0xf bank_mask:0xf
	v_fmac_f32_dpp v118, v30, v102 row_shl:14 row_mask:0xf bank_mask:0xf
	v_fmac_f32_dpp v119, v31, v103 row_shl:14 row_mask:0xf bank_mask:0xf
	v_fmac_f32_dpp v120, v32, v104 row_shl:14 row_mask:0xf bank_mask:0xf
	v_fmac_f32_dpp v121, v33, v105 row_shl:14 row_mask:0xf bank_mask:0xf
	v_fmac_f32_dpp v122, v26, v98 row_shl:14 row_mask:0xf bank_mask:0xf
	v_fmac_f32_dpp v123, v27, v99 row_shl:14 row_mask:0xf bank_mask:0xf
	v_fmac_f32_dpp v124, v28, v100 row_shl:14 row_mask:0xf bank_mask:0xf
	v_fmac_f32_dpp v125, v29, v101 row_shl:14 row_mask:0xf bank_mask:0xf
	v_pk_mul_f32 v[126:127], v[118:119], v[118:119]
	v_pk_mul_f32 v[128:129], v[120:121], v[120:121]
	v_pk_fma_f32 v[126:127], v[126:127], v[132:133], v[196:197] op_sel_hi:[1,0,0]
	v_pk_fma_f32 v[128:129], v[128:129], v[132:133], v[196:197] op_sel_hi:[1,0,0]
	v_pk_mul_f32 v[126:127], v[118:119], v[126:127]
	v_pk_mul_f32 v[128:129], v[120:121], v[128:129]
	v_exp_f32_e32 v126, v126
	v_exp_f32_e32 v127, v127
	v_exp_f32_e32 v128, v128
	v_exp_f32_e32 v129, v129
	v_pk_add_f32 v[126:127], v[126:127], v[250:251] op_sel_hi:[1,0]
	v_pk_add_f32 v[128:129], v[128:129], v[250:251] op_sel_hi:[1,0]
	v_rcp_f32_e32 v126, v126
	v_rcp_f32_e32 v127, v127
	v_rcp_f32_e32 v128, v128
	v_rcp_f32_e32 v129, v129
	v_pk_mul_f32 v[126:127], v[118:119], v[126:127]
	v_pk_mul_f32 v[128:129], v[120:121], v[128:129]
	v_pk_mul_f32 v[126:127], v[122:123], v[126:127]
	v_pk_mul_f32 v[128:129], v[124:125], v[128:129]
	v_cvt_pk_bf16_f32 v126, v126, v127
	v_cvt_pk_bf16_f32 v127, v128, v129
	v_add_u32_e32 v131, 0x18c000, v199
	global_store_dwordx2 v131, v[126:127], s[68:69] offset:8
	v_pk_mul_f32 v[14:15], v[14:15], v[200:201] op_sel_hi:[1,0]
	v_pk_mul_f32 v[16:17], v[16:17], v[200:201] op_sel_hi:[1,0]
	v_pk_mul_f32 v[10:11], v[10:11], v[200:201] op_sel_hi:[1,0]
	v_pk_mul_f32 v[12:13], v[12:13], v[200:201] op_sel_hi:[1,0]
	v_pk_fma_f32 v[106:107], v[14:15], v[154:155], v[150:151]
	v_pk_fma_f32 v[108:109], v[16:17], v[156:157], v[152:153]
	v_pk_fma_f32 v[110:111], v[10:11], v[134:135], v[146:147]
	v_pk_fma_f32 v[112:113], v[12:13], v[136:137], v[148:149]
	v_fmac_f32_dpp v106, v14, v142 row_shr:1 row_mask:0xf bank_mask:0xf
	v_fmac_f32_dpp v107, v15, v143 row_shr:1 row_mask:0xf bank_mask:0xf
; __device__ __forceinline__ unsigned cvt_pk_bf16(float lo, float hi) { unsigned r; asm volatile("v_cvt_pk_bf16_f32 %0, %1, %2" : "=v"(r) : "v"(lo), "v"(hi)); return r; }
; __device__ __forceinline__ f32x4 gelu4(f32x4 v) { return (f32x4){gelu_t(v[0]), gelu_t(v[1]), gelu_t(v[2]), gelu_t(v[3])}; }
; template <int CTRL> __device__ __forceinline__ f32x4 dpp4(f32x4 v) { return (f32x4){dpp_f<CTRL>(v[0]), dpp_f<CTRL>(v[1]), dpp_f<CTRL>(v[2]), dpp_f<CTRL>(v[3])}; }
; #define PG8_BAR __builtin_amdgcn_s_barrier()
;     __device__ __forceinline__ void operator()(const f32x4 (&acc)[2][2][4][2], const Unit& u, int wr, int wc, int fr, int fq) const {
;     ...
;                     for (int m = 0; m < 4; ++m) {
;                         const f32x4 g = acc[ai][0][m][n] * rs[ai][m], v = acc[ai][1][m][n] * rs[ai][m];
;                         const f32x4 g1 = dpp4<0x121>(g), g2 = dpp4<0x122>(g), v1 = dpp4<0x121>(v), v2 = dpp4<0x122>(v);
;                         const f32x4 gp1 = (fr >= 1) ? g1 : pg1, gp2 = (fr >= 2) ? g2 : pg2, vp1 = (fr >= 1) ? v1 : pv1, vp2 = (fr >= 2) ? v2 : pv2;
;                         const f32x4 cgt = bg + wg0 * g + wg1 * gp1 + wg2 * gp2, cvl = bv + wv0 * v + wv1 * vp1 + wv2 * vp2;
;                         const f32x4 o = gelu4(cgt) * cvl;
;                         typedef unsigned u32x2e __attribute__((ext_vector_type(2)));
;                         u32x2e w; w.x = cvt_pk_bf16(o[0], o[1]); w.y = cvt_pk_bf16(o[2], o[3]);
;                         if (!(m == 0 && fr < 2)) *(u32x2e*)((bf16_t*)O + (size_t)(row0 + ai * HALF + m * 16) * DFFc + c) = w;
; template <class Epi, class Sched, bool ALIGN_EPI = false, bool SP2 = false>
; __device__ __forceinline__ void gemm_phase(PG8_LAS unsigned char* lds, const Gemm g, const Sched& S, const Epi& E, int wave_in) {
;     ...
;         if constexpr (ALIGN_EPI) { if (wr == 0) PG8_BAR; }
;         if constexpr (!Epi::AFTER_DRAIN) { E(acc, cur, wr, wc, fr, fq); S.done(cur); }
;         if (!has_next) break;
	v_fmac_f32_dpp v108, v16, v144 row_shr:1 row_mask:0xf bank_mask:0xf
	v_fmac_f32_dpp v109, v17, v145 row_shr:1 row_mask:0xf bank_mask:0xf
	v_fmac_f32_dpp v110, v10, v138 row_shr:1 row_mask:0xf bank_mask:0xf
	v_fmac_f32_dpp v111, v11, v139 row_shr:1 row_mask:0xf bank_mask:0xf
	v_fmac_f32_dpp v112, v12, v140 row_shr:1 row_mask:0xf bank_mask:0xf
	v_fmac_f32_dpp v113, v13, v141 row_shr:1 row_mask:0xf bank_mask:0xf
	v_fmac_f32_dpp v106, v14, v102 row_shr:2 row_mask:0xf bank_mask:0xf
	v_fmac_f32_dpp v107, v15, v103 row_shr:2 row_mask:0xf bank_mask:0xf
	v_fmac_f32_dpp v108, v16, v104 row_shr:2 row_mask:0xf bank_mask:0xf
	v_fmac_f32_dpp v109, v17, v105 row_shr:2 row_mask:0xf bank_mask:0xf
	v_fmac_f32_dpp v110, v10, v98 row_shr:2 row_mask:0xf bank_mask:0xf
	v_fmac_f32_dpp v111, v11, v99 row_shr:2 row_mask:0xf bank_mask:0xf
	v_fmac_f32_dpp v112, v12, v100 row_shr:2 row_mask:0xf bank_mask:0xf
	v_fmac_f32_dpp v113, v13, v101 row_shr:2 row_mask:0xf bank_mask:0xf
	v_fmac_f32_dpp v106, v22, v142 row_shl:15 row_mask:0xf bank_mask:0xf
	v_fmac_f32_dpp v107, v23, v143 row_shl:15 row_mask:0xf bank_mask:0xf
	v_fmac_f32_dpp v108, v24, v144 row_shl:15 row_mask:0xf bank_mask:0xf
	v_fmac_f32_dpp v109, v25, v145 row_shl:15 row_mask:0xf bank_mask:0xf
	v_fmac_f32_dpp v110, v18, v138 row_shl:15 row_mask:0xf bank_mask:0xf
	v_fmac_f32_dpp v111, v19, v139 row_shl:15 row_mask:0xf bank_mask:0xf
	v_fmac_f32_dpp v112, v20, v140 row_shl:15 row_mask:0xf bank_mask:0xf
	v_fmac_f32_dpp v113, v21, v141 row_shl:15 row_mask:0xf bank_mask:0xf
	v_fmac_f32_dpp v106, v22, v102 row_shl:14 row_mask:0xf bank_mask:0xf
	v_fmac_f32_dpp v107, v23, v103 row_shl:14 row_mask:0xf bank_mask:0xf
	v_fmac_f32_dpp v108, v24, v104 row_shl:14 row_mask:0xf bank_mask:0xf
	v_fmac_f32_dpp v109, v25, v105 row_shl:14 row_mask:0xf bank_mask:0xf
	v_fmac_f32_dpp v110, v18, v98 row_shl:14 row_mask:0xf bank_mask:0xf
	v_fmac_f32_dpp v111, v19, v99 row_shl:14 row_mask:0xf bank_mask:0xf
	v_fmac_f32_dpp v112, v20, v100 row_shl:14 row_mask:0xf bank_mask:0xf
	v_fmac_f32_dpp v113, v21, v101 row_shl:14 row_mask:0xf bank_mask:0xf
	v_pk_mul_f32 v[114:115], v[106:107], v[106:107]
	v_pk_mul_f32 v[116:117], v[108:109], v[108:109]
	v_pk_fma_f32 v[114:115], v[114:115], v[132:133], v[196:197] op_sel_hi:[1,0,0]
	v_pk_fma_f32 v[116:117], v[116:117], v[132:133], v[196:197] op_sel_hi:[1,0,0]
	v_pk_mul_f32 v[114:115], v[106:107], v[114:115]
	v_pk_mul_f32 v[116:117], v[108:109], v[116:117]
	v_exp_f32_e32 v114, v114
	v_exp_f32_e32 v115, v115
	v_exp_f32_e32 v116, v116
	v_exp_f32_e32 v117, v117
	v_pk_add_f32 v[114:115], v[114:115], v[250:251] op_sel_hi:[1,0]
	v_pk_add_f32 v[116:117], v[116:117], v[250:251] op_sel_hi:[1,0]
	v_rcp_f32_e32 v114, v114
	v_rcp_f32_e32 v115, v115
	v_rcp_f32_e32 v116, v116
	v_rcp_f32_e32 v117, v117
	v_pk_mul_f32 v[114:115], v[106:107], v[114:115]
	v_pk_mul_f32 v[116:117], v[108:109], v[116:117]
	v_pk_mul_f32 v[114:115], v[110:111], v[114:115]
	v_pk_mul_f32 v[116:117], v[112:113], v[116:117]
	v_cvt_pk_bf16_f32 v114, v114, v115
	v_cvt_pk_bf16_f32 v115, v116, v117
	v_add_u32_e32 v130, 0x1b8000, v199
	global_store_dwordx2 v130, v[114:115], s[68:69] offset:8
	v_pk_mul_f32 v[6:7], v[6:7], v[178:179] op_sel_hi:[1,0]
	v_pk_mul_f32 v[8:9], v[8:9], v[178:179] op_sel_hi:[1,0]
	v_pk_mul_f32 v[2:3], v[2:3], v[178:179] op_sel_hi:[1,0]
	v_pk_mul_f32 v[4:5], v[4:5], v[178:179] op_sel_hi:[1,0]
	v_pk_fma_f32 v[118:119], v[6:7], v[154:155], v[150:151]
	v_pk_fma_f32 v[120:121], v[8:9], v[156:157], v[152:153]
	v_pk_fma_f32 v[122:123], v[2:3], v[134:135], v[146:147]
	v_pk_fma_f32 v[124:125], v[4:5], v[136:137], v[148:149]
	v_fmac_f32_dpp v118, v6, v142 row_shr:1 row_mask:0xf bank_mask:0xf
	v_fmac_f32_dpp v119, v7, v143 row_shr:1 row_mask:0xf bank_mask:0xf
	v_fmac_f32_dpp v120, v8, v144 row_shr:1 row_mask:0xf bank_mask:0xf
	v_fmac_f32_dpp v121, v9, v145 row_shr:1 row_mask:0xf bank_mask:0xf
	v_fmac_f32_dpp v122, v2, v138 row_shr:1 row_mask:0xf bank_mask:0xf
	v_fmac_f32_dpp v123, v3, v139 row_shr:1 row_mask:0xf bank_mask:0xf
	v_fmac_f32_dpp v124, v4, v140 row_shr:1 row_mask:0xf bank_mask:0xf
	v_fmac_f32_dpp v125, v5, v141 row_shr:1 row_mask:0xf bank_mask:0xf
	v_fmac_f32_dpp v118, v6, v102 row_shr:2 row_mask:0xf bank_mask:0xf
	v_fmac_f32_dpp v119, v7, v103 row_shr:2 row_mask:0xf bank_mask:0xf
	v_fmac_f32_dpp v120, v8, v104 row_shr:2 row_mask:0xf bank_mask:0xf
	v_fmac_f32_dpp v121, v9, v105 row_shr:2 row_mask:0xf bank_mask:0xf
	v_fmac_f32_dpp v122, v2, v98 row_shr:2 row_mask:0xf bank_mask:0xf
	v_fmac_f32_dpp v123, v3, v99 row_shr:2 row_mask:0xf bank_mask:0xf
	v_fmac_f32_dpp v124, v4, v100 row_shr:2 row_mask:0xf bank_mask:0xf
	v_fmac_f32_dpp v125, v5, v101 row_shr:2 row_mask:0xf bank_mask:0xf
	v_fmac_f32_dpp v118, v14, v142 row_shl:15 row_mask:0xf bank_mask:0xf
	v_fmac_f32_dpp v119, v15, v143 row_shl:15 row_mask:0xf bank_mask:0xf
	v_fmac_f32_dpp v120, v16, v144 row_shl:15 row_mask:0xf bank_mask:0xf
	v_fmac_f32_dpp v121, v17, v145 row_shl:15 row_mask:0xf bank_mask:0xf
	v_fmac_f32_dpp v122, v10, v138 row_shl:15 row_mask:0xf bank_mask:0xf
	v_fmac_f32_dpp v123, v11, v139 row_shl:15 row_mask:0xf bank_mask:0xf
	v_fmac_f32_dpp v124, v12, v140 row_shl:15 row_mask:0xf bank_mask:0xf
	v_fmac_f32_dpp v125, v13, v141 row_shl:15 row_mask:0xf bank_mask:0xf
	v_fmac_f32_dpp v118, v14, v102 row_shl:14 row_mask:0xf bank_mask:0xf
	v_fmac_f32_dpp v119, v15, v103 row_shl:14 row_mask:0xf bank_mask:0xf
	v_fmac_f32_dpp v120, v16, v104 row_shl:14 row_mask:0xf bank_mask:0xf
	v_fmac_f32_dpp v121, v17, v105 row_shl:14 row_mask:0xf bank_mask:0xf
	v_fmac_f32_dpp v122, v10, v98 row_shl:14 row_mask:0xf bank_mask:0xf
	v_fmac_f32_dpp v123, v11, v99 row_shl:14 row_mask:0xf bank_mask:0xf
	v_fmac_f32_dpp v124, v12, v100 row_shl:14 row_mask:0xf bank_mask:0xf
	v_fmac_f32_dpp v125, v13, v101 row_shl:14 row_mask:0xf bank_mask:0xf
	v_pk_mul_f32 v[126:127], v[118:119], v[118:119]
	v_pk_mul_f32 v[128:129], v[120:121], v[120:121]
	v_pk_fma_f32 v[126:127], v[126:127], v[132:133], v[196:197] op_sel_hi:[1,0,0]
	v_pk_fma_f32 v[128:129], v[128:129], v[132:133], v[196:197] op_sel_hi:[1,0,0]
	v_pk_mul_f32 v[126:127], v[118:119], v[126:127]
	v_pk_mul_f32 v[128:129], v[120:121], v[128:129]
	v_exp_f32_e32 v126, v126
	v_exp_f32_e32 v127, v127
	v_exp_f32_e32 v128, v128
	v_exp_f32_e32 v129, v129
	v_pk_add_f32 v[126:127], v[126:127], v[250:251] op_sel_hi:[1,0]
	v_pk_add_f32 v[128:129], v[128:129], v[250:251] op_sel_hi:[1,0]
	v_rcp_f32_e32 v126, v126
	v_rcp_f32_e32 v127, v127
	v_rcp_f32_e32 v128, v128
	v_rcp_f32_e32 v129, v129
	v_pk_mul_f32 v[126:127], v[118:119], v[126:127]
	v_pk_mul_f32 v[128:129], v[120:121], v[128:129]
	v_pk_mul_f32 v[126:127], v[122:123], v[126:127]
	v_pk_mul_f32 v[128:129], v[124:125], v[128:129]
	v_cvt_pk_bf16_f32 v126, v126, v127
	v_cvt_pk_bf16_f32 v127, v128, v129
	v_add_u32_e32 v131, 0x1e4000, v199
	global_store_dwordx2 v131, v[126:127], s[68:69] offset:8
	s_andn2_b64 vcc, exec, s[8:9]
	s_mov_b64 s[8:9], -1
	s_cbranch_vccnz .LBB0_39
	s_andn2_b64 vcc, exec, s[2:3]
	s_cbranch_vccnz .LBB0_38
	s_barrier
	s_branch .LBB0_38

; template <class Epi, class Sched, bool ALIGN_EPI = false, bool SP2 = false>
; __device__ __forceinline__ void gemm_phase(PG8_LAS unsigned char* lds, const Gemm g, const Sched& S, const Epi& E, int wave_in) {
;     ...
;         const char* nA = has_next ? (const char*)g.A + (size_t)nxt.pm * tstepA : cA; const char* nB = has_next ? (const char*)g.Bt + (size_t)nxt.pn * tstep : cB;
;         for (int t = 0; t < nt; t += 2) {
;             const bool last = (t == nt - 2);
;             const char* a1 = cA + (size_t)(t + 1) * kstep;
;             const char* a2 = last ? nA : cA + (size_t)(t + 2) * kstep; const char* b2 = last ? nB : cB + (size_t)(t + 2) * kstep;
;             const char* a3 = a2 + kstep; const char* b3 = b2 + kstep;
;     ...
; #pragma unroll
;         for (int a = 0; a < 2; ++a)
; #pragma unroll
;             for (int b = 0; b < 2; ++b)
; #pragma unroll
;                 for (int m = 0; m < 4; ++m)
; #pragma unroll
;                     for (int n = 0; n < 2; ++n) acc[a][b][m][n] = (f32x4){0.f, 0.f, 0.f, 0.f};
;         cur = nxt; cA = nA; cB = nB; ++ui;
.LBB0_83:
	s_ashr_i32 s17, s16, 31
	s_lshl_b64 s[18:19], s[16:17], 20
	v_readlane_b32 s20, v253, 62
	v_readlane_b32 s21, v253, 63
	s_add_u32 s18, s20, s18
	s_addc_u32 s19, s21, s19
	s_and_b64 s[20:21], s[4:5], exec
	s_cselect_b32 s17, s19, s23
	s_cselect_b32 s42, s18, s22
	s_ashr_i32 s11, s10, 31
	s_lshl_b64 s[20:21], s[10:11], 19
	s_add_u32 s20, s28, s20
	s_addc_u32 s21, s29, s21
	s_and_b64 s[26:27], s[4:5], exec
	s_cselect_b32 s11, s21, s25
	s_cselect_b32 s43, s20, s24
	s_add_u32 s22, s22, 0x80080
	s_addc_u32 s23, s23, 0
	s_add_u32 s44, s24, 0x100
	v_mov_b32_e32 v2, 0
	s_addc_u32 s45, s25, 0
	s_mov_b32 s46, -2
	v_mov_b32_e32 v3, v2
	v_mov_b32_e32 v4, v2
	v_mov_b32_e32 v5, v2
	v_mov_b32_e32 v6, v2
	v_mov_b32_e32 v7, v2
	v_mov_b32_e32 v8, v2
	v_mov_b32_e32 v9, v2
	v_mov_b32_e32 v14, v2
	v_mov_b32_e32 v15, v2
	v_mov_b32_e32 v16, v2
	v_mov_b32_e32 v17, v2
	v_mov_b32_e32 v18, v2
	v_mov_b32_e32 v19, v2
	s_waitcnt vmcnt(0)
	v_mov_b32_e32 v20, v2
	v_mov_b32_e32 v21, v2
	v_mov_b32_e32 v30, v2
	v_mov_b32_e32 v31, v2
	v_mov_b32_e32 v32, v2
	v_mov_b32_e32 v33, v2
	v_mov_b32_e32 v34, v2
	v_mov_b32_e32 v35, v2
	v_mov_b32_e32 v36, v2
	v_mov_b32_e32 v37, v2
	v_mov_b32_e32 v46, v2
	v_mov_b32_e32 v47, v2
	v_mov_b32_e32 v48, v2
	v_mov_b32_e32 v49, v2
	v_mov_b32_e32 v50, v2
	v_mov_b32_e32 v51, v2
	v_mov_b32_e32 v52, v2
	v_mov_b32_e32 v53, v2
	v_mov_b32_e32 v10, v2
	v_mov_b32_e32 v11, v2
	v_mov_b32_e32 v12, v2
	v_mov_b32_e32 v13, v2
	v_mov_b32_e32 v22, v2
	v_mov_b32_e32 v23, v2
	v_mov_b32_e32 v24, v2
	v_mov_b32_e32 v25, v2
	v_mov_b32_e32 v26, v2
	v_mov_b32_e32 v27, v2
	v_mov_b32_e32 v28, v2
	v_mov_b32_e32 v29, v2
	v_mov_b32_e32 v38, v2
	v_mov_b32_e32 v39, v2
	v_mov_b32_e32 v40, v2
	v_mov_b32_e32 v41, v2
	v_mov_b32_e32 v42, v2
	v_mov_b32_e32 v43, v2
	v_mov_b32_e32 v44, v2
	v_mov_b32_e32 v45, v2
	v_mov_b32_e32 v54, v2
	v_mov_b32_e32 v55, v2
	v_mov_b32_e32 v56, v2
	v_mov_b32_e32 v57, v2
	v_mov_b32_e32 v58, v2
	v_mov_b32_e32 v59, v2
	v_mov_b32_e32 v60, v2
	v_mov_b32_e32 v61, v2
	v_mov_b32_e32 v62, v2
	v_mov_b32_e32 v63, v2
	v_mov_b32_e32 v64, v2
	v_mov_b32_e32 v65, v2
	v_mov_b32_e32 v66, v2
	v_mov_b32_e32 v67, v2
	v_mov_b32_e32 v68, v2
	v_mov_b32_e32 v69, v2
	v_mov_b32_e32 v70, v2
	v_mov_b32_e32 v71, v2
	v_mov_b32_e32 v72, v2
	v_mov_b32_e32 v73, v2
	v_mov_b32_e32 v78, v2
	v_mov_b32_e32 v79, v2
	v_mov_b32_e32 v80, v2
	v_mov_b32_e32 v81, v2
	v_mov_b32_e32 v82, v2
	v_mov_b32_e32 v83, v2
	v_mov_b32_e32 v84, v2
	v_mov_b32_e32 v85, v2
	v_mov_b32_e32 v94, v2
	v_mov_b32_e32 v95, v2
	v_mov_b32_e32 v96, v2
	v_mov_b32_e32 v97, v2
	v_mov_b32_e32 v98, v2
	v_mov_b32_e32 v99, v2
	v_mov_b32_e32 v100, v2
	v_mov_b32_e32 v101, v2
	v_mov_b32_e32 v110, v2
	v_mov_b32_e32 v111, v2
	v_mov_b32_e32 v112, v2
	v_mov_b32_e32 v113, v2
	v_mov_b32_e32 v114, v2
	v_mov_b32_e32 v115, v2
	v_mov_b32_e32 v116, v2
	v_mov_b32_e32 v117, v2
	v_mov_b32_e32 v74, v2
	v_mov_b32_e32 v75, v2
	v_mov_b32_e32 v76, v2
	v_mov_b32_e32 v77, v2
	v_mov_b32_e32 v86, v2
	v_mov_b32_e32 v87, v2
	v_mov_b32_e32 v88, v2
	v_mov_b32_e32 v89, v2
	v_mov_b32_e32 v90, v2
	v_mov_b32_e32 v91, v2
	v_mov_b32_e32 v92, v2
	v_mov_b32_e32 v93, v2
	v_mov_b32_e32 v102, v2
	v_mov_b32_e32 v103, v2
	v_mov_b32_e32 v104, v2
	v_mov_b32_e32 v105, v2
	v_mov_b32_e32 v106, v2
	v_mov_b32_e32 v107, v2
	v_mov_b32_e32 v108, v2
	v_mov_b32_e32 v109, v2
	v_mov_b32_e32 v118, v2
	v_mov_b32_e32 v119, v2
	v_mov_b32_e32 v120, v2
	v_mov_b32_e32 v121, v2
	v_mov_b32_e32 v122, v2
	v_mov_b32_e32 v123, v2
	v_mov_b32_e32 v124, v2
	v_mov_b32_e32 v125, v2
	v_mov_b32_e32 v126, v2
	v_mov_b32_e32 v127, v2
	v_mov_b32_e32 v128, v2
	v_mov_b32_e32 v129, v2
	s_nop 0
	s_nop 0
	s_nop 0
	s_nop 0
	s_nop 0
	s_nop 0
	s_nop 0
	s_nop 0
	s_nop 0
	s_nop 0
	s_nop 0
